# passA loop rotated: next unit q/k/v/GLRP loads issued after staging barrier into dedicated regs, w2 column cached in regs
# speedup vs baseline: 1.0037x; 1.0037x over previous
; #define LAS __attribute__((address_space(3)))
; __device__ __forceinline__ void gla_passA(LAS unsigned char* lds, int uidx, const bf16_t* PR, const float* GLRP, const float* w2, const float* gb,
;                                           bf16_t* SUB, float* EB, bf16_t* QT, bf16_t* AM, int tid, int wid, int lane) {
;     const int b = uidx >> 7, c = (uidx >> 2) & 31, h = uidx & 3; const int tok0 = b * SEQ + c * 64; const int bh = b * 4 + h;
;     LAS float* Bc = (LAS float*)lds;
;     LAS float* bCs = Bc + 64 * 129;
;     LAS bf16_t* Qs = (LAS bf16_t*)(lds + 33536);
;     LAS bf16_t* Ks = Qs + 64 * 136;
;     LAS bf16_t* Kh = Ks + 64 * 136;
;     LAS bf16_t* Vn = Kh + 64 * 136;
;     const int r = lane & 15, q = lane >> 4;
;     const bf16_t* qp = PR + (size_t)(tok0 + (tid >> 3)) * PRW + 1024 + h * DK + (tid & 7) * 16;
;     const u32x4 qa = *(const u32x4*)qp, qb = *(const u32x4*)(qp + 8), ka = *(const u32x4*)(qp + 512), kb = *(const u32x4*)(qp + 520);
;     u32x4 vreg[4];
; #pragma unroll
;     for (int i = 0; i < 4; ++i) { const int id = tid + 512 * i; vreg[i] = *(const u32x4*)(PR + (size_t)(tok0 + (id >> 5)) * PRW + 2048 + h * DV + (id & 31) * 8); }
;     LAS float* Gs = (LAS float*)(lds + 120576);
;     LAS float* Tt = Gs + 64 * 16;
;     if (tid < 256) { const int t = tid >> 2, r4 = (tid & 3) * 4; const float* gp = GLRP + (size_t)(tok0 + t) * RANK + r4; f32x4 g = *(const f32x4*)gp;
; #pragma unroll
;         for (int sp = 1; sp < NSP1; ++sp) g += *(const f32x4*)(gp + (size_t)sp * MPAD * RANK);
;         *(LAS f32x4*)(Gs + t * 16 + r4) = g; }
;     const int kcol = tid & 127, tg = tid >> 7;
;     float wk[16];
; #pragma unroll
;     for (int rr = 0; rr < 16; ++rr) wk[rr] = w2[rr * QKD + h * DK + kcol];
;     const float bias = gb[h * DK + kcol];
.LBB0_346:
	s_or_b64 exec, exec, s[0:1]
	v_readlane_b32 s0, v244, 13
	v_readlane_b32 s1, v244, 14
	s_xor_b64 s[0:1], s[0:1], -1
	s_mov_b64 s[26:27], s[90:91]
	v_mov_b32_e32 v112, v210
	v_writelane_b32 v244, s0, 30
	s_waitcnt lgkmcnt(0)
	s_barrier
	s_load_dwordx4 s[28:31], s[26:27], 0x40
	s_load_dwordx2 s[2:3], s[26:27], 0x50
	v_writelane_b32 v244, s1, 31
	v_readfirstlane_b32 s6, v112
	v_readlane_b32 s0, v244, 32
	v_readlane_b32 s1, v244, 33
	s_lshl_b64 s[22:23], s[0:1], 11
	s_ashr_i32 s8, s6, 6
	s_waitcnt lgkmcnt(0)
	s_add_u32 s4, s28, s4
	s_addc_u32 s5, s29, s5
	s_movk_i32 s7, 0x100
	v_readlane_b32 s0, v245, 19
	s_add_u32 s38, s30, s22
	v_cmp_gt_i32_e64 s[40:41], s7, v112
	s_movk_i32 s7, 0x7f
	v_readlane_b32 s1, v245, 20
	v_and_b32_e32 v110, 63, v112
	s_addc_u32 s39, s31, s23
	v_lshlrev_b32_e32 v120, 2, v112
	v_cmp_lt_i32_e64 s[42:43], s7, v112
	v_ashrrev_i32_e32 v113, 31, v112
	s_and_b64 vcc, exec, s[0:1]
	s_cbranch_vccz .LBB0_357
	v_lshlrev_b32_e32 v0, 4, v112
	v_and_b32_e32 v0, 0x70, v0
	v_readlane_b32 s7, v245, 60
	v_lshlrev_b32_e32 v6, 2, v0
	v_ashrrev_i32_e32 v111, 3, v112
	v_lshl_add_u32 v122, v112, 2, s7
	v_add_u32_e32 v123, s7, v6
	v_readlane_b32 s7, v245, 61
	v_ashrrev_i32_e32 v4, 7, v112
	v_cmp_lt_i32_e64 s[44:45], 0, v4
	v_add_u32_e32 v124, s7, v6
	v_readlane_b32 s7, v245, 62
	v_cmp_lt_i32_e64 s[46:47], 1, v4
	v_cmp_lt_i32_e64 s[48:49], 2, v4
	v_add_u32_e32 v125, s7, v6
	v_readlane_b32 s7, v245, 63
	s_movk_i32 s23, 0x110
	s_lshl_b32 s22, s8, 5
	v_add_u32_e32 v126, s7, v6
	s_movk_i32 s7, 0x204
	v_mul_lo_u32 v4, v111, s7
	v_add3_u32 v127, 0, v4, v6
	v_mul_lo_u32 v4, v111, s23
	v_lshlrev_b32_e32 v6, 1, v0
	v_readlane_b32 s10, v244, 0
	v_and_b32_e32 v10, 15, v112
	s_and_b32 s7, s22, 32
	s_lshl_b32 s9, s8, 3
	v_add3_u32 v128, 0, v4, v6
	v_add3_u32 v129, s10, v4, v6
	v_bfi_b32 v11, -16, s9, v112
	v_or_b32_e32 v6, s7, v10
	s_or_b32 s9, s7, 16
	v_mul_u32_u24_e32 v13, 0x110, v6
	v_or_b32_e32 v6, s9, v10
	v_mul_u32_u24_e32 v15, 0x110, v6
	v_lshrrev_b32_e32 v6, 2, v110
	v_and_b32_e32 v6, 12, v6
	v_lshlrev_b32_e32 v1, 3, v112
	v_or_b32_e32 v8, s7, v6
	v_and_b32_e32 v2, 0xf8, v1
	v_add_u32_e32 v1, 0x200, v112
	v_or_b32_e32 v12, 2, v8
	v_ashrrev_i32_e32 v115, 5, v1
	v_add_u32_e32 v1, 0x400, v112
	v_cmp_gt_i32_e64 s[54:55], v12, v11
	v_or_b32_e32 v12, 3, v8
	v_ashrrev_i32_e32 v116, 5, v1
	v_add_u32_e32 v1, 0x600, v112
	v_ashrrev_i32_e32 v118, 2, v112
	v_lshlrev_b32_e32 v3, 2, v120
	v_cmp_gt_i32_e64 s[56:57], v12, v11
	v_or_b32_e32 v12, s9, v6
	v_ashrrev_i32_e32 v117, 5, v1
	v_lshlrev_b32_e32 v1, 6, v118
	v_and_b32_e32 v168, 48, v3
	v_readlane_b32 s0, v245, 58
	v_or_b32_e32 v14, 2, v12
	v_cmp_gt_i32_e64 s[62:63], v14, v11
	v_add3_u32 v119, s0, v1, v168
	v_readlane_b32 s0, v245, 59
	v_lshlrev_b32_e32 v14, 1, v10
	s_movk_i32 s1, 0x220
	v_and_b32_e32 v4, 48, v110
	v_cmp_gt_i32_e64 s[58:59], v12, v11
	v_cmp_lt_i32_e64 s[60:61], v12, v11
	v_or_b32_e32 v12, 3, v12
	v_add_u32_e32 v16, s0, v14
	v_add_u32_e32 v14, s10, v14
	s_and_b32 s10, s6, 0xffffffc0
	s_load_dwordx2 s[6:7], s[26:27], 0x98
	v_mul_lo_u32 v5, v115, s1
	v_add_u32_e32 v4, 0, v4
	v_cmp_gt_i32_e64 s[64:65], v12, v11
	v_lshrrev_b32_e32 v12, 1, v112
	v_mad_u64_u32 v[80:81], s[24:25], v11, s23, v[4:5]
	v_and_b32_e32 v12, 24, v12
	v_mad_u32_u24 v17, v12, s1, v16
	v_mad_u32_u24 v81, v12, s23, v14
	v_or_b32_e32 v12, 32, v12
	v_mad_u32_u24 v130, v12, s23, v14
	s_ashr_i32 s23, s22, 31
	s_waitcnt lgkmcnt(0)
	s_add_u32 s24, s6, 0x12900000
	s_addc_u32 s25, s7, 0
	s_add_u32 s28, s6, 0x1ad84000
	s_addc_u32 s29, s7, 0
	s_add_u32 s9, s6, 0x1ed84000
	v_lshlrev_b32_e32 v26, 6, v11
	s_addc_u32 s30, s7, 0
	v_ashrrev_i32_e32 v27, 31, v26
	s_add_u32 s34, s6, 0x1edc4000
	s_addc_u32 s35, s7, 0
	v_lshl_add_u64 v[28:29], s[6:7], 0, v[168:169]
	v_lshl_add_u64 v[26:27], v[26:27], 1, s[6:7]
	s_mov_b64 s[6:7], 0x1f5c4000
	v_ashrrev_i32_e32 v114, 5, v112
	v_cmp_gt_i32_e64 s[50:51], v8, v11
	v_cmp_lt_i32_e64 s[52:53], v8, v11
	v_lshlrev_b32_e32 v10, 8, v10
	v_lshl_add_u64 v[84:85], v[26:27], 0, s[6:7]
	v_lshrrev_b32_e32 v11, 4, v111
	s_movk_i32 s6, 0x2040
	v_and_b32_e32 v121, 0x7f, v112
	v_lshl_add_u32 v1, v2, 1, s0
	v_mul_lo_u32 v3, v114, s1
	v_mul_lo_u32 v7, v116, s1
	v_mul_lo_u32 v9, v117, s1
	v_mad_u32_u24 v19, v12, s1, v16
	v_or_b32_e32 v12, 0x1000, v10
	v_or_b32_e32 v14, 0x2000, v10
	v_or_b32_e32 v16, 0x3000, v10
	v_or_b32_e32 v18, 0x4000, v10
	v_or_b32_e32 v20, 0x5000, v10
	v_or_b32_e32 v22, 0x6000, v10
	v_or_b32_e32 v24, 0x7000, v10
	s_mov_b64 s[66:67], 0x212c4000
	v_mul_lo_u32 v21, v11, s6
	v_lshl_add_u64 v[82:83], v[28:29], 0, s[66:67]
	v_lshl_add_u32 v131, v121, 2, v21
	v_lshlrev_b32_e32 v132, 10, v11
	v_lshlrev_b32_e32 v86, 1, v2
	v_add_u32_e32 v133, v1, v3
	v_add_u32_e32 v134, v1, v5
	v_add_u32_e32 v135, v1, v7
	v_add_u32_e32 v136, v1, v9
	v_lshlrev_b32_e32 v168, 1, v0
	v_add_u32_e32 v137, v4, v13
	v_add_u32_e32 v138, v4, v15
	v_lshlrev_b32_e32 v88, 1, v8
	v_add_u32_e32 v139, s10, v17
	v_add_u32_e32 v140, s10, v19
	v_lshlrev_b32_e32 v90, 1, v6
	v_lshlrev_b32_e32 v92, 1, v10
	v_lshlrev_b32_e32 v94, 1, v12
	v_lshlrev_b32_e32 v96, 1, v14
	v_lshlrev_b32_e32 v98, 1, v16
	v_lshlrev_b32_e32 v100, 1, v18
	v_lshlrev_b32_e32 v102, 1, v20
	v_lshlrev_b32_e32 v104, 1, v22
	v_lshlrev_b32_e32 v106, 1, v24
	v_readlane_b32 s66, v245, 52
	v_readlane_b32 s67, v245, 53
	v_lshrrev_b32_e32 v247, 3, v112
	v_and_b32_e32 v248, 7, v112
	v_lshlrev_b32_e32 v247, 13, v247
	v_lshl_or_b32 v247, v248, 5, v247
	v_lshrrev_b32_e32 v248, 5, v112
	v_and_b32_e32 v249, 31, v112
	v_lshlrev_b32_e32 v248, 13, v248
	v_lshl_or_b32 v248, v249, 4, v248
	v_and_b32_e32 v249, 0xff, v112
	v_lshlrev_b32_e32 v249, 4, v249
	s_mov_b32 s72, -1
	s_mov_b32 s98, s66
; __device__ __forceinline__ unsigned cvt_pk_bf16(float lo, float hi) { unsigned r; asm volatile("v_cvt_pk_bf16_f32 %0, %1, %2" : "=v"(r) : "v"(lo), "v"(hi)); return r; }
; #define LAS __attribute__((address_space(3)))
; #define MFMA16(x, y, c) __builtin_amdgcn_mfma_f32_16x16x32_bf16((x), (y), (c), 0, 0, 0)
; __device__ __forceinline__ void gla_passA(LAS unsigned char* lds, int uidx, const bf16_t* PR, const float* GLRP, const float* w2, const float* gb,
;                                           bf16_t* SUB, float* EB, bf16_t* QT, bf16_t* AM, int tid, int wid, int lane) {
;     ...
;     const bf16_t* qp = PR + (size_t)(tok0 + (tid >> 3)) * PRW + 1024 + h * DK + (tid & 7) * 16;
;     const u32x4 qa = *(const u32x4*)qp, qb = *(const u32x4*)(qp + 8), ka = *(const u32x4*)(qp + 512), kb = *(const u32x4*)(qp + 520);
;     u32x4 vreg[4];
; #pragma unroll
;     for (int i = 0; i < 4; ++i) { const int id = tid + 512 * i; vreg[i] = *(const u32x4*)(PR + (size_t)(tok0 + (id >> 5)) * PRW + 2048 + h * DV + (id & 31) * 8); }
;     LAS float* Gs = (LAS float*)(lds + 120576);
;     LAS float* Tt = Gs + 64 * 16;
;     if (tid < 256) { const int t = tid >> 2, r4 = (tid & 3) * 4; const float* gp = GLRP + (size_t)(tok0 + t) * RANK + r4; f32x4 g = *(const f32x4*)gp;
; #pragma unroll
;         for (int sp = 1; sp < NSP1; ++sp) g += *(const f32x4*)(gp + (size_t)sp * MPAD * RANK);
;         *(LAS f32x4*)(Gs + t * 16 + r4) = g; }
;     ...
;         const int it = wid >> 1, jt0 = (wid & 1) * 2; f32x4 a[2] = {{0.f, 0.f, 0.f, 0.f}, {0.f, 0.f, 0.f, 0.f}};
; #pragma unroll
;         for (int ks = 0; ks < 4; ++ks) { const bf16x8 y = *(const LAS bf16x8*)(Qs + (16 * it + r) * 136 + 32 * ks + 8 * q);
; #pragma unroll
;             for (int jj = 0; jj < 2; ++jj) { const bf16x8 x = *(const LAS bf16x8*)(Ks + (16 * (jt0 + jj) + r) * 136 + 32 * ks + 8 * q); a[jj] = MFMA16(x, y, a[jj]); } }
;         const int i = 16 * it + r;
; #pragma unroll
;         for (int jj = 0; jj < 2; ++jj) { const int jb = 16 * (jt0 + jj) + 4 * q; u32x2 w;
;             w.x = cvt_pk_bf16(jb + 0 <= i ? a[jj][0] : 0.f, jb + 1 <= i ? a[jj][1] : 0.f); w.y = cvt_pk_bf16(jb + 2 <= i ? a[jj][2] : 0.f, jb + 3 <= i ? a[jj][3] : 0.f);
;             *(u32x2*)(AM + (size_t)uidx * 4096 + i * 64 + jb) = w; }
	s_ashr_i32 s99, s98, 7
	s_lshl_b32 s99, s99, 11
	s_bfe_u32 s100, s98, 0x50002
	s_lshl_b32 s100, s100, 6
	s_or_b32 s99, s99, s100
	s_and_b32 s98, s98, 3
	s_lshl_b32 s73, s98, 8
	s_lshl_b32 s100, s99, 13
	s_add_u32 s100, s100, s73
	s_add_u32 s100, s24, s100
	s_addc_u32 s101, s25, 0
	global_load_dwordx4 v[178:181], v247, s[100:101] offset:2048
	global_load_dwordx4 v[182:185], v247, s[100:101] offset:2064
	global_load_dwordx4 v[186:189], v247, s[100:101] offset:3072
	global_load_dwordx4 v[190:193], v247, s[100:101] offset:3088
	s_add_u32 s73, s73, 0x1000
	s_add_u32 s100, s100, s73
	s_addc_u32 s101, s101, 0
	global_load_dwordx4 v[194:197], v248, s[100:101]
	s_add_u32 s100, s100, 0x20000
	s_addc_u32 s101, s101, 0
	global_load_dwordx4 v[198:201], v248, s[100:101]
	s_add_u32 s100, s100, 0x20000
	s_addc_u32 s101, s101, 0
	global_load_dwordx4 v[202:205], v248, s[100:101]
	s_add_u32 s100, s100, 0x20000
	s_addc_u32 s101, s101, 0
	global_load_dwordx4 v[206:209], v248, s[100:101]
	s_lshl_b32 s99, s99, 6
	s_add_u32 s100, s24, 0x0e9c4000
	s_addc_u32 s101, s25, 0
	s_add_u32 s100, s100, s99
	s_addc_u32 s101, s101, 0
	global_load_dwordx4 v[142:145], v249, s[100:101]
	s_add_u32 s100, s100, 0x84000
	s_addc_u32 s101, s101, 0
	global_load_dwordx4 v[146:149], v249, s[100:101]
	s_add_u32 s100, s100, 0x84000
	s_addc_u32 s101, s101, 0
	global_load_dwordx4 v[150:153], v249, s[100:101]
	s_add_u32 s100, s100, 0x84000
	s_addc_u32 s101, s101, 0
	global_load_dwordx4 v[154:157], v249, s[100:101]
	s_waitcnt vmcnt(0)
	s_branch .LBB0_349
.LBB0_348:
	s_or_b64 exec, exec, s[6:7]
	s_waitcnt lgkmcnt(0)
	s_barrier
	ds_read_b128 v[0:3], v80 offset:33536
	ds_read_b128 v[4:7], v137 offset:50944
	ds_read_b128 v[8:11], v138 offset:50944
	s_waitcnt lgkmcnt(1)
	v_mfma_f32_16x16x32_bf16 v[4:7], v[4:7], v[0:3], 0
	s_ashr_i32 s67, s66, 31
	s_lshl_b64 s[6:7], s[66:67], 13
	v_mov_b32_e32 v89, v169
	s_waitcnt lgkmcnt(0)
	v_mfma_f32_16x16x32_bf16 v[0:3], v[8:11], v[0:3], 0
	ds_read_b128 v[8:11], v80 offset:33600
	ds_read_b128 v[12:15], v137 offset:51008
	s_lshl_b32 s10, s31, 16
	v_mov_b32_e32 v105, v169
	s_waitcnt lgkmcnt(0)
	v_mfma_f32_16x16x32_bf16 v[4:7], v[12:15], v[8:11], v[4:7]
	ds_read_b128 v[12:15], v138 offset:51008
	v_mov_b32_e32 v107, v169
	s_add_i32 s66, s66, s82
	s_waitcnt lgkmcnt(0)
	v_mfma_f32_16x16x32_bf16 v[0:3], v[12:15], v[8:11], v[0:3]
	ds_read_b128 v[8:11], v80 offset:33664
	ds_read_b128 v[12:15], v137 offset:51072
	s_cmpk_gt_i32 s66, 0x1ff
	s_waitcnt lgkmcnt(0)
	v_mfma_f32_16x16x32_bf16 v[4:7], v[12:15], v[8:11], v[4:7]
	ds_read_b128 v[12:15], v138 offset:51072
	s_waitcnt lgkmcnt(0)
	v_mfma_f32_16x16x32_bf16 v[0:3], v[12:15], v[8:11], v[0:3]
	ds_read_b128 v[8:11], v80 offset:33728
	ds_read_b128 v[12:15], v137 offset:51136
	s_waitcnt lgkmcnt(0)
	v_mfma_f32_16x16x32_bf16 v[4:7], v[12:15], v[8:11], v[4:7]
	ds_read_b128 v[12:15], v138 offset:51136
	s_waitcnt lgkmcnt(0)
	v_mfma_f32_16x16x32_bf16 v[0:3], v[12:15], v[8:11], v[0:3]
	s_nop 4
	v_cndmask_b32_e64 v4, v4, 0, s[50:51]
	v_cndmask_b32_e64 v5, 0, v5, s[52:53]
	v_lshl_add_u64 v[8:9], v[84:85], 0, s[6:7]
	v_cvt_pk_bf16_f32 v4, v4, v5
	v_cndmask_b32_e64 v5, v6, 0, s[54:55]
	v_cndmask_b32_e64 v6, v7, 0, s[56:57]
	v_cvt_pk_bf16_f32 v5, v5, v6
	v_lshl_add_u64 v[6:7], v[8:9], 0, v[88:89]
	v_cndmask_b32_e64 v0, v0, 0, s[58:59]
	v_cndmask_b32_e64 v1, 0, v1, s[60:61]
	global_store_dwordx2 v[6:7], v[4:5], off
	v_cvt_pk_bf16_f32 v0, v0, v1
	v_cndmask_b32_e64 v1, v2, 0, s[62:63]
	v_cndmask_b32_e64 v2, v3, 0, s[64:65]
	v_cvt_pk_bf16_f32 v1, v1, v2
	global_store_dwordx2 v[6:7], v[0:1], off offset:32
	ds_read_u16 v0, v139
	ds_read_u16 v4, v139 offset:544
	ds_read_u16 v1, v139 offset:1088
	ds_read_u16 v5, v139 offset:1632
	ds_read_u16 v2, v139 offset:2176
	ds_read_u16 v6, v139 offset:2720
	ds_read_u16 v3, v139 offset:3264
	ds_read_u16 v7, v139 offset:3808
	ds_read_u16 v12, v139 offset:32
	ds_read_u16 v13, v139 offset:576
	ds_read_u16 v14, v139 offset:1120
	ds_read_u16 v15, v139 offset:1664
	ds_read_u16 v16, v139 offset:2208
	ds_read_u16 v17, v139 offset:2752
	ds_read_u16 v18, v139 offset:3296
	ds_read_u16 v19, v139 offset:3840
	ds_read_u16 v8, v81 offset:272
	ds_read_u16 v9, v81 offset:544
	ds_read_u16 v20, v81 offset:816
	ds_read_u16 v10, v81 offset:1088
	ds_read_u16 v21, v81 offset:1360
	ds_read_u16 v11, v81 offset:1632
	ds_read_u16 v22, v81 offset:1904
	s_waitcnt lgkmcnt(4)
	v_perm_b32 v9, v20, v9, s13
	v_perm_b32 v67, v19, v18, s13
	s_waitcnt lgkmcnt(2)
	v_perm_b32 v10, v21, v10, s13
	ds_read_u16 v20, v81
	ds_read_u16 v21, v81 offset:32
	v_perm_b32 v66, v17, v16, s13
	v_perm_b32 v65, v15, v14, s13
	v_perm_b32 v64, v13, v12, s13
	ds_read_u16 v12, v81 offset:304
	ds_read_u16 v13, v81 offset:576
	ds_read_u16 v14, v81 offset:848
	ds_read_u16 v15, v81 offset:1120
	ds_read_u16 v16, v81 offset:1392
	ds_read_u16 v17, v81 offset:1664
	ds_read_u16 v18, v81 offset:1936
	s_waitcnt lgkmcnt(9)
	v_perm_b32 v11, v22, v11, s13
	s_waitcnt lgkmcnt(8)
	v_perm_b32 v8, v8, v20, s13
	v_perm_b32 v3, v7, v3, s13
	v_perm_b32 v2, v6, v2, s13
	s_waitcnt lgkmcnt(0)
; #define LAS __attribute__((address_space(3)))
; #define MFMA16(x, y, c) __builtin_amdgcn_mfma_f32_16x16x32_bf16((x), (y), (c), 0, 0, 0)
; template <int RS> __device__ __forceinline__ bf16x8 tr_frag(const LAS bf16_t* T, int c, int ks, int lane) {
;     ...
;     const int g = lane >> 4; const LAS bf16_t* a0 = T + (32 * ks + 8 * g) * RS + 16 * c + (lane & 15); bf16x8 o;
; #pragma unroll
;     for (int j = 0; j < 8; ++j) o[j] = (short)a0[j * RS];
; __device__ __forceinline__ void gla_passA(LAS unsigned char* lds, int uidx, const bf16_t* PR, const float* GLRP, const float* w2, const float* gb,
;                                           bf16_t* SUB, float* EB, bf16_t* QT, bf16_t* AM, int tid, int wid, int lane) {
;     ...
; #pragma unroll
;         for (int ks = 0; ks < 2; ++ks) { bf16x8 x[2];
; #pragma unroll
;             for (int a = 0; a < 2; ++a) x[a] = tr_frag<272>(Vn, 2 * wid + a, ks, lane);
; #pragma unroll
;             for (int yt = 0; yt < 8; ++yt) { const bf16x8 y = tr_frag<136>(Kh, yt, ks, lane);
; #pragma unroll
;                 for (int a = 0; a < 2; ++a) acc[a][yt] = MFMA16(x[a], y, acc[a][yt]); } }
	v_perm_b32 v19, v18, v17, s13
	v_perm_b32 v18, v16, v15, s13
	v_perm_b32 v16, v12, v21, s13
	ds_read_u16 v20, v81 offset:64
	ds_read_u16 v21, v81 offset:336
	ds_read_u16 v22, v81 offset:608
	ds_read_u16 v23, v81 offset:880
	ds_read_u16 v24, v81 offset:1152
	ds_read_u16 v25, v81 offset:1424
	ds_read_u16 v26, v81 offset:1696
	ds_read_u16 v27, v81 offset:1968
	ds_read_u16 v28, v81 offset:96
	ds_read_u16 v29, v81 offset:368
	ds_read_u16 v30, v81 offset:640
	ds_read_u16 v31, v81 offset:912
	ds_read_u16 v32, v81 offset:1184
	ds_read_u16 v33, v81 offset:1456
	ds_read_u16 v34, v81 offset:1728
	ds_read_u16 v35, v81 offset:2000
	ds_read_u16 v36, v81 offset:128
	ds_read_u16 v37, v81 offset:400
	ds_read_u16 v38, v81 offset:672
	ds_read_u16 v39, v81 offset:944
	ds_read_u16 v40, v81 offset:1216
	ds_read_u16 v41, v81 offset:1488
	ds_read_u16 v42, v81 offset:1760
	ds_read_u16 v43, v81 offset:2032
	ds_read_u16 v44, v81 offset:160
	ds_read_u16 v45, v81 offset:432
	ds_read_u16 v46, v81 offset:704
	ds_read_u16 v47, v81 offset:976
	ds_read_u16 v48, v81 offset:1248
	ds_read_u16 v49, v81 offset:1520
	ds_read_u16 v50, v81 offset:1792
	ds_read_u16 v51, v81 offset:2064
	ds_read_u16 v52, v81 offset:192
	ds_read_u16 v53, v81 offset:464
	ds_read_u16 v54, v81 offset:736
	ds_read_u16 v55, v81 offset:1008
	ds_read_u16 v56, v81 offset:1280
	ds_read_u16 v57, v81 offset:1552
	ds_read_u16 v58, v81 offset:1824
	ds_read_u16 v59, v81 offset:2096
	ds_read_u16 v60, v81 offset:224
	ds_read_u16 v61, v81 offset:496
	ds_read_u16 v62, v81 offset:768
	ds_read_u16 v63, v81 offset:1040
	ds_read_u16 v68, v81 offset:1312
	ds_read_u16 v69, v81 offset:1584
	ds_read_u16 v70, v81 offset:1856
	ds_read_u16 v71, v81 offset:2128
	v_perm_b32 v1, v5, v1, s13
	v_perm_b32 v0, v4, v0, s13
	v_perm_b32 v17, v14, v13, s13
	s_waitcnt lgkmcnt(14)
	v_perm_b32 v27, v27, v26, s13
	v_perm_b32 v26, v25, v24, s13
	v_perm_b32 v25, v23, v22, s13
	v_perm_b32 v24, v21, v20, s13
	v_perm_b32 v35, v35, v34, s13
	v_perm_b32 v34, v33, v32, s13
	v_perm_b32 v33, v31, v30, s13
	v_perm_b32 v32, v29, v28, s13
	v_perm_b32 v43, v43, v42, s13
	v_perm_b32 v42, v41, v40, s13
	v_perm_b32 v41, v39, v38, s13
	v_perm_b32 v40, v37, v36, s13
	v_perm_b32 v51, v51, v50, s13
	v_perm_b32 v50, v49, v48, s13
	v_perm_b32 v49, v47, v46, s13
	v_perm_b32 v48, v45, v44, s13
	s_waitcnt lgkmcnt(8)
	v_perm_b32 v59, v59, v58, s13
	v_perm_b32 v58, v57, v56, s13
	v_perm_b32 v57, v55, v54, s13
	v_perm_b32 v56, v53, v52, s13
	s_waitcnt lgkmcnt(0)
	v_perm_b32 v71, v71, v70, s13
	v_perm_b32 v70, v69, v68, s13
	v_perm_b32 v69, v63, v62, s13
	v_perm_b32 v68, v61, v60, s13
	v_mfma_f32_16x16x32_bf16 v[4:7], v[0:3], v[8:11], 0
	v_mfma_f32_16x16x32_bf16 v[8:11], v[64:67], v[8:11], 0
	v_mfma_f32_16x16x32_bf16 v[12:15], v[0:3], v[16:19], 0
	v_mfma_f32_16x16x32_bf16 v[16:19], v[64:67], v[16:19], 0
	v_mfma_f32_16x16x32_bf16 v[20:23], v[0:3], v[24:27], 0
	v_mfma_f32_16x16x32_bf16 v[24:27], v[64:67], v[24:27], 0
	v_mfma_f32_16x16x32_bf16 v[28:31], v[0:3], v[32:35], 0
	v_mfma_f32_16x16x32_bf16 v[32:35], v[64:67], v[32:35], 0
	v_mfma_f32_16x16x32_bf16 v[36:39], v[0:3], v[40:43], 0
	v_mfma_f32_16x16x32_bf16 v[40:43], v[64:67], v[40:43], 0
	v_mfma_f32_16x16x32_bf16 v[44:47], v[0:3], v[48:51], 0
	v_mfma_f32_16x16x32_bf16 v[48:51], v[64:67], v[48:51], 0
	v_mfma_f32_16x16x32_bf16 v[52:55], v[0:3], v[56:59], 0
	v_mfma_f32_16x16x32_bf16 v[56:59], v[64:67], v[56:59], 0
	v_mfma_f32_16x16x32_bf16 v[60:63], v[0:3], v[68:71], 0
	v_mfma_f32_16x16x32_bf16 v[0:3], v[64:67], v[68:71], 0
	ds_read_u16 v64, v140 offset:544
	ds_read_u16 v65, v140 offset:1088
	ds_read_u16 v66, v140 offset:1632
	ds_read_u16 v67, v140 offset:2176
	ds_read_u16 v68, v140 offset:2720
	ds_read_u16 v69, v140 offset:3264
	ds_read_u16 v70, v140 offset:3808
	ds_read_u16 v71, v140
	ds_read_u16 v87, v140 offset:32
	ds_read_u16 v89, v140 offset:576
	ds_read_u16 v91, v140 offset:1120
	ds_read_u16 v93, v140 offset:1664
	ds_read_u16 v95, v140 offset:2208
	ds_read_u16 v97, v140 offset:2752
	ds_read_u16 v99, v140 offset:3296
	ds_read_u16 v101, v140 offset:3840
	ds_read_u16 v72, v130 offset:272
	ds_read_u16 v73, v130 offset:544
	ds_read_u16 v74, v130 offset:816
	ds_read_u16 v75, v130 offset:1088
	ds_read_u16 v76, v130 offset:1360
	ds_read_u16 v77, v130 offset:1632
	ds_read_u16 v78, v130 offset:1904
	s_waitcnt lgkmcnt(0)
	v_perm_b32 v79, v78, v77, s13
	v_perm_b32 v77, v74, v73, s13
	ds_read_u16 v73, v130
	ds_read_u16 v103, v130 offset:32
	v_perm_b32 v78, v76, v75, s13
	v_perm_b32 v75, v70, v69, s13
	v_perm_b32 v74, v68, v67, s13
	s_waitcnt lgkmcnt(1)
	v_perm_b32 v76, v72, v73, s13
	v_perm_b32 v73, v66, v65, s13
	v_perm_b32 v72, v64, v71, s13
	v_perm_b32 v71, v101, v99, s13
	v_perm_b32 v70, v97, v95, s13
	v_perm_b32 v69, v93, v91, s13
	v_perm_b32 v68, v89, v87, s13
	v_mfma_f32_16x16x32_bf16 v[64:67], v[72:75], v[76:79], v[4:7]
	v_mov_b32_e32 v91, v169
	v_mov_b32_e32 v93, v169
	v_mov_b32_e32 v95, v169
	v_mfma_f32_16x16x32_bf16 v[4:7], v[68:71], v[76:79], v[8:11]
	s_nop 2
	ds_read_u16 v8, v130 offset:304
	ds_read_u16 v9, v130 offset:576
	ds_read_u16 v76, v130 offset:848
	ds_read_u16 v10, v130 offset:1120
	ds_read_u16 v77, v130 offset:1392
	ds_read_u16 v11, v130 offset:1664
	ds_read_u16 v78, v130 offset:1936
	s_waitcnt lgkmcnt(4)
	v_perm_b32 v9, v76, v9, s13
	v_perm_b32 v8, v8, v103, s13
	s_waitcnt lgkmcnt(2)
	v_perm_b32 v10, v77, v10, s13
	v_mov_b32_e32 v97, v169
	s_waitcnt lgkmcnt(0)
; __device__ __forceinline__ unsigned cvt_pk_bf16(float lo, float hi) { unsigned r; asm volatile("v_cvt_pk_bf16_f32 %0, %1, %2" : "=v"(r) : "v"(lo), "v"(hi)); return r; }
; #define MFMA16(x, y, c) __builtin_amdgcn_mfma_f32_16x16x32_bf16((x), (y), (c), 0, 0, 0)
; __device__ __forceinline__ void gla_passA(LAS unsigned char* lds, int uidx, const bf16_t* PR, const float* GLRP, const float* w2, const float* gb,
;                                           bf16_t* SUB, float* EB, bf16_t* QT, bf16_t* AM, int tid, int wid, int lane) {
;     ...
;             for (int yt = 0; yt < 8; ++yt) { const bf16x8 y = tr_frag<136>(Kh, yt, ks, lane);
; #pragma unroll
;                 for (int a = 0; a < 2; ++a) acc[a][yt] = MFMA16(x[a], y, acc[a][yt]); } }
;         bf16_t* sp = SUB + ((size_t)bh * NCH + c) * (DK * DV);
; #pragma unroll
;         for (int a = 0; a < 2; ++a)
; #pragma unroll
;             for (int yt = 0; yt < 8; ++yt) { u32x2 w; w.x = cvt_pk_bf16(acc[a][yt][0], acc[a][yt][1]); w.y = cvt_pk_bf16(acc[a][yt][2], acc[a][yt][3]); *(u32x2*)(sp + (16 * yt + r) * DV + 32 * wid + 16 * a + 4 * q) = w; }
;     }
;     __syncthreads();
	v_perm_b32 v11, v78, v11, s13
	v_mov_b32_e32 v99, v169
	v_mov_b32_e32 v101, v169
	v_mfma_f32_16x16x32_bf16 v[76:79], v[72:75], v[8:11], v[12:15]
	v_mov_b32_e32 v103, v169
	v_mfma_f32_16x16x32_bf16 v[8:11], v[68:71], v[8:11], v[16:19]
	s_nop 0
	ds_read_u16 v12, v130 offset:64
	s_nop 0
	ds_read_u16 v16, v130 offset:336
	ds_read_u16 v13, v130 offset:608
	ds_read_u16 v17, v130 offset:880
	ds_read_u16 v14, v130 offset:1152
	ds_read_u16 v18, v130 offset:1424
	ds_read_u16 v15, v130 offset:1696
	ds_read_u16 v19, v130 offset:1968
	s_waitcnt lgkmcnt(4)
	v_perm_b32 v13, v17, v13, s13
	v_perm_b32 v12, v16, v12, s13
	s_waitcnt lgkmcnt(2)
	v_perm_b32 v14, v18, v14, s13
	s_waitcnt lgkmcnt(0)
	v_perm_b32 v15, v19, v15, s13
	s_nop 1
	v_mfma_f32_16x16x32_bf16 v[20:23], v[72:75], v[12:15], v[20:23]
	v_mfma_f32_16x16x32_bf16 v[12:15], v[68:71], v[12:15], v[24:27]
	ds_read_u16 v16, v130 offset:96
	s_nop 1
	ds_read_u16 v24, v130 offset:368
	ds_read_u16 v17, v130 offset:640
	ds_read_u16 v25, v130 offset:912
	ds_read_u16 v18, v130 offset:1184
	ds_read_u16 v26, v130 offset:1456
	ds_read_u16 v19, v130 offset:1728
	ds_read_u16 v27, v130 offset:2000
	s_waitcnt lgkmcnt(4)
	v_perm_b32 v17, v25, v17, s13
	v_perm_b32 v16, v24, v16, s13
	s_waitcnt lgkmcnt(2)
	v_perm_b32 v18, v26, v18, s13
	s_waitcnt lgkmcnt(0)
	v_perm_b32 v19, v27, v19, s13
	s_nop 1
	v_mfma_f32_16x16x32_bf16 v[28:31], v[72:75], v[16:19], v[28:31]
	v_mfma_f32_16x16x32_bf16 v[16:19], v[68:71], v[16:19], v[32:35]
	ds_read_u16 v24, v130 offset:128
	s_nop 1
	ds_read_u16 v32, v130 offset:400
	ds_read_u16 v25, v130 offset:672
	ds_read_u16 v33, v130 offset:944
	ds_read_u16 v26, v130 offset:1216
	ds_read_u16 v34, v130 offset:1488
	ds_read_u16 v27, v130 offset:1760
	ds_read_u16 v35, v130 offset:2032
	s_waitcnt lgkmcnt(4)
	v_perm_b32 v25, v33, v25, s13
	v_perm_b32 v24, v32, v24, s13
	s_waitcnt lgkmcnt(2)
	v_perm_b32 v26, v34, v26, s13
	s_waitcnt lgkmcnt(0)
	v_perm_b32 v27, v35, v27, s13
	s_nop 1
	v_mfma_f32_16x16x32_bf16 v[36:39], v[72:75], v[24:27], v[36:39]
	v_mfma_f32_16x16x32_bf16 v[24:27], v[68:71], v[24:27], v[40:43]
	ds_read_u16 v32, v130 offset:160
	s_nop 1
	ds_read_u16 v40, v130 offset:432
	ds_read_u16 v33, v130 offset:704
	ds_read_u16 v41, v130 offset:976
	ds_read_u16 v34, v130 offset:1248
	ds_read_u16 v42, v130 offset:1520
	ds_read_u16 v35, v130 offset:1792
	ds_read_u16 v43, v130 offset:2064
	s_waitcnt lgkmcnt(4)
	v_perm_b32 v33, v41, v33, s13
	v_perm_b32 v32, v40, v32, s13
	s_waitcnt lgkmcnt(2)
	v_perm_b32 v34, v42, v34, s13
	s_waitcnt lgkmcnt(0)
	v_perm_b32 v35, v43, v35, s13
	s_nop 1
	v_mfma_f32_16x16x32_bf16 v[44:47], v[72:75], v[32:35], v[44:47]
	v_mfma_f32_16x16x32_bf16 v[32:35], v[68:71], v[32:35], v[48:51]
	ds_read_u16 v40, v130 offset:192
	s_nop 1
	ds_read_u16 v48, v130 offset:464
	ds_read_u16 v41, v130 offset:736
	ds_read_u16 v49, v130 offset:1008
	ds_read_u16 v42, v130 offset:1280
	ds_read_u16 v50, v130 offset:1552
	ds_read_u16 v43, v130 offset:1824
	ds_read_u16 v51, v130 offset:2096
	s_waitcnt lgkmcnt(4)
	v_perm_b32 v41, v49, v41, s13
	v_perm_b32 v40, v48, v40, s13
	s_waitcnt lgkmcnt(2)
	v_perm_b32 v42, v50, v42, s13
	s_waitcnt lgkmcnt(0)
	v_perm_b32 v43, v51, v43, s13
	s_nop 1
	v_mfma_f32_16x16x32_bf16 v[48:51], v[72:75], v[40:43], v[52:55]
	v_mfma_f32_16x16x32_bf16 v[40:43], v[68:71], v[40:43], v[56:59]
	s_nop 1
	ds_read_u16 v52, v130 offset:224
	ds_read_u16 v56, v130 offset:496
	ds_read_u16 v53, v130 offset:768
	ds_read_u16 v57, v130 offset:1040
	ds_read_u16 v54, v130 offset:1312
	ds_read_u16 v58, v130 offset:1584
	ds_read_u16 v55, v130 offset:1856
	ds_read_u16 v59, v130 offset:2128
	s_waitcnt lgkmcnt(4)
	v_perm_b32 v53, v57, v53, s13
	v_perm_b32 v52, v56, v52, s13
	s_waitcnt lgkmcnt(2)
	v_perm_b32 v54, v58, v54, s13
	s_waitcnt lgkmcnt(0)
	v_perm_b32 v55, v59, v55, s13
	s_nop 1
	v_mfma_f32_16x16x32_bf16 v[56:59], v[72:75], v[52:55], v[60:63]
	v_mfma_f32_16x16x32_bf16 v[0:3], v[68:71], v[52:55], v[0:3]
	v_lshlrev_b64 v[52:53], 21, v[108:109]
	v_lshl_add_u64 v[52:53], s[28:29], 0, v[52:53]
	v_lshl_add_u64 v[52:53], v[52:53], 0, s[10:11]
	v_lshl_add_u64 v[52:53], s[22:23], 1, v[52:53]
	v_lshl_add_u64 v[52:53], v[52:53], 0, v[90:91]
	v_cvt_pk_bf16_f32 v54, v64, v65
	v_cvt_pk_bf16_f32 v55, v66, v67
	v_lshl_add_u64 v[60:61], v[52:53], 0, v[92:93]
	v_lshl_add_u64 v[62:63], v[52:53], 0, v[94:95]
	global_store_dwordx2 v[60:61], v[54:55], off
	v_cvt_pk_bf16_f32 v54, v76, v77
	v_cvt_pk_bf16_f32 v55, v78, v79
	global_store_dwordx2 v[62:63], v[54:55], off
	v_cvt_pk_bf16_f32 v20, v20, v21
	v_cvt_pk_bf16_f32 v21, v22, v23
	v_lshl_add_u64 v[22:23], v[52:53], 0, v[96:97]
	global_store_dwordx2 v[22:23], v[20:21], off
	v_cvt_pk_bf16_f32 v20, v28, v29
	v_cvt_pk_bf16_f32 v21, v30, v31
	v_lshl_add_u64 v[22:23], v[52:53], 0, v[98:99]
	global_store_dwordx2 v[22:23], v[20:21], off
	v_cvt_pk_bf16_f32 v20, v36, v37
	v_cvt_pk_bf16_f32 v21, v38, v39
	v_lshl_add_u64 v[22:23], v[52:53], 0, v[100:101]
	global_store_dwordx2 v[22:23], v[20:21], off
	v_cvt_pk_bf16_f32 v20, v44, v45
	v_cvt_pk_bf16_f32 v21, v46, v47
	v_lshl_add_u64 v[22:23], v[52:53], 0, v[102:103]
	global_store_dwordx2 v[22:23], v[20:21], off
	v_cvt_pk_bf16_f32 v20, v48, v49
	v_cvt_pk_bf16_f32 v21, v50, v51
	v_lshl_add_u64 v[22:23], v[52:53], 0, v[104:105]
	global_store_dwordx2 v[22:23], v[20:21], off
	v_cvt_pk_bf16_f32 v20, v56, v57
	v_cvt_pk_bf16_f32 v21, v58, v59
	v_lshl_add_u64 v[22:23], v[52:53], 0, v[106:107]
	global_store_dwordx2 v[22:23], v[20:21], off
	v_lshl_add_u64 v[20:21], v[52:53], 0, 32
	v_cvt_pk_bf16_f32 v4, v4, v5
	v_cvt_pk_bf16_f32 v5, v6, v7
	v_lshl_add_u64 v[6:7], v[20:21], 0, v[94:95]
	global_store_dwordx2 v[60:61], v[4:5], off offset:32
	v_cvt_pk_bf16_f32 v4, v8, v9
	v_cvt_pk_bf16_f32 v5, v10, v11
	global_store_dwordx2 v[6:7], v[4:5], off
	v_lshl_add_u64 v[6:7], v[20:21], 0, v[96:97]
	v_cvt_pk_bf16_f32 v4, v12, v13
	v_cvt_pk_bf16_f32 v5, v14, v15
	global_store_dwordx2 v[6:7], v[4:5], off
	v_lshl_add_u64 v[6:7], v[20:21], 0, v[98:99]
	v_cvt_pk_bf16_f32 v4, v16, v17
	v_cvt_pk_bf16_f32 v5, v18, v19
	global_store_dwordx2 v[6:7], v[4:5], off
	v_lshl_add_u64 v[6:7], v[20:21], 0, v[100:101]
	v_cvt_pk_bf16_f32 v4, v24, v25
	v_cvt_pk_bf16_f32 v5, v26, v27
	global_store_dwordx2 v[6:7], v[4:5], off
	v_lshl_add_u64 v[6:7], v[20:21], 0, v[102:103]
	v_cvt_pk_bf16_f32 v4, v32, v33
	v_cvt_pk_bf16_f32 v5, v34, v35
	global_store_dwordx2 v[6:7], v[4:5], off
	v_lshl_add_u64 v[6:7], v[20:21], 0, v[104:105]
	v_cvt_pk_bf16_f32 v4, v40, v41
	v_cvt_pk_bf16_f32 v5, v42, v43
	global_store_dwordx2 v[6:7], v[4:5], off
	v_cvt_pk_bf16_f32 v0, v0, v1
	v_cvt_pk_bf16_f32 v1, v2, v3
	v_lshl_add_u64 v[2:3], v[20:21], 0, v[106:107]
	global_store_dwordx2 v[2:3], v[0:1], off
	s_barrier
	s_waitcnt vmcnt(20)
	s_cbranch_scc1 .LBB0_357
; #define LAS __attribute__((address_space(3)))
; __device__ __forceinline__ void gla_passA(LAS unsigned char* lds, int uidx, const bf16_t* PR, const float* GLRP, const float* w2, const float* gb,
;                                           bf16_t* SUB, float* EB, bf16_t* QT, bf16_t* AM, int tid, int wid, int lane) {
;     ...
;     const bf16_t* qp = PR + (size_t)(tok0 + (tid >> 3)) * PRW + 1024 + h * DK + (tid & 7) * 16;
;     const u32x4 qa = *(const u32x4*)qp, qb = *(const u32x4*)(qp + 8), ka = *(const u32x4*)(qp + 512), kb = *(const u32x4*)(qp + 520);
;     u32x4 vreg[4];
; #pragma unroll
;     for (int i = 0; i < 4; ++i) { const int id = tid + 512 * i; vreg[i] = *(const u32x4*)(PR + (size_t)(tok0 + (id >> 5)) * PRW + 2048 + h * DV + (id & 31) * 8); }
;     LAS float* Gs = (LAS float*)(lds + 120576);
;     LAS float* Tt = Gs + 64 * 16;
;     if (tid < 256) { const int t = tid >> 2, r4 = (tid & 3) * 4; const float* gp = GLRP + (size_t)(tok0 + t) * RANK + r4; f32x4 g = *(const f32x4*)gp;
; #pragma unroll
;         for (int sp = 1; sp < NSP1; ++sp) g += *(const f32x4*)(gp + (size_t)sp * MPAD * RANK);
;         *(LAS f32x4*)(Gs + t * 16 + r4) = g; }
;     const int kcol = tid & 127, tg = tid >> 7;
;     float wk[16];
; #pragma unroll
;     for (int rr = 0; rr < 16; ++rr) wk[rr] = w2[rr * QKD + h * DK + kcol];
;     const float bias = gb[h * DK + kcol];
; #pragma unroll
;     for (int i = 0; i < 4; ++i) { const int id = tid + 512 * i; *(LAS u32x4*)(Vn + (id >> 5) * 272 + (id & 31) * 8) = vreg[i]; }
;     __syncthreads();
.LBB0_349:
	s_ashr_i32 s67, s66, 7
	s_bfe_u32 s31, s66, 0x50002
	s_lshl_b32 s6, s67, 11
	s_lshl_b32 s7, s31, 6
	s_or_b32 s69, s7, s6
	v_add_u32_e32 v32, s69, v111
	v_ashrrev_i32_e32 v33, 31, v32
	v_add_u32_e32 v16, s69, v114
	s_and_b32 s68, s66, 3
	v_lshlrev_b64 v[0:1], 13, v[32:33]
	v_ashrrev_i32_e32 v17, 31, v16
	v_lshl_add_u64 v[0:1], s[24:25], 0, v[0:1]
	s_lshl_b32 s10, s68, 8
	v_lshlrev_b64 v[16:17], 13, v[16:17]
	v_add_u32_e32 v18, s69, v115
	v_lshl_add_u64 v[0:1], v[0:1], 0, s[10:11]
	v_lshl_add_u64 v[16:17], s[24:25], 0, v[16:17]
	s_lshl_b32 s10, s68, 9
	v_ashrrev_i32_e32 v19, 31, v18
	v_lshl_add_u64 v[16:17], v[16:17], 0, s[10:11]
	v_mov_b32_e32 v87, v169
	v_lshlrev_b64 v[18:19], 13, v[18:19]
	v_add_u32_e32 v24, s69, v116
	v_lshl_add_u64 v[16:17], v[16:17], 0, v[86:87]
	v_lshl_add_u64 v[18:19], s[24:25], 0, v[18:19]
	v_ashrrev_i32_e32 v25, 31, v24
	v_add_co_u32_e32 v16, vcc, s15, v16
	v_lshl_add_u64 v[18:19], v[18:19], 0, s[10:11]
	v_lshlrev_b64 v[24:25], 13, v[24:25]
	v_add_u32_e32 v26, s69, v117
	v_addc_co_u32_e32 v17, vcc, 0, v17, vcc
	v_lshl_add_u64 v[18:19], v[18:19], 0, v[86:87]
	v_lshl_add_u64 v[24:25], s[24:25], 0, v[24:25]
	v_ashrrev_i32_e32 v27, 31, v26
	v_add_co_u32_e32 v20, vcc, s15, v18
	v_lshl_add_u64 v[24:25], v[24:25], 0, s[10:11]
	v_lshlrev_b64 v[26:27], 13, v[26:27]
	v_addc_co_u32_e32 v21, vcc, 0, v19, vcc
	v_lshl_add_u64 v[24:25], v[24:25], 0, v[86:87]
	v_lshl_add_u64 v[26:27], s[24:25], 0, v[26:27]
	v_add_co_u32_e32 v24, vcc, s15, v24
	v_lshl_add_u64 v[26:27], v[26:27], 0, s[10:11]
	v_lshl_add_u64 v[8:9], v[0:1], 0, v[168:169]
	v_addc_co_u32_e32 v25, vcc, 0, v25, vcc
	v_lshl_add_u64 v[26:27], v[26:27], 0, v[86:87]
	v_mov_b32_e32 v4, v182
	v_mov_b32_e32 v5, v183
	v_mov_b32_e32 v6, v184
	v_mov_b32_e32 v7, v185
	v_mov_b32_e32 v12, v178
	v_mov_b32_e32 v13, v179
	v_mov_b32_e32 v14, v180
	v_mov_b32_e32 v15, v181
	v_mov_b32_e32 v0, v190
	v_mov_b32_e32 v1, v191
	v_mov_b32_e32 v2, v192
	v_mov_b32_e32 v3, v193
	v_mov_b32_e32 v8, v186
	v_mov_b32_e32 v9, v187
	v_mov_b32_e32 v10, v188
	v_mov_b32_e32 v11, v189
	s_and_saveexec_b64 s[6:7], s[40:41]
	s_cbranch_execz .LBB0_351
	v_pk_add_f32 v[146:147], v[142:143], v[146:147]
	v_pk_add_f32 v[148:149], v[144:145], v[148:149]
	v_pk_add_f32 v[146:147], v[146:147], v[150:151]
	v_pk_add_f32 v[148:149], v[148:149], v[152:153]
	v_pk_add_f32 v[146:147], v[146:147], v[154:155]
	v_pk_add_f32 v[148:149], v[148:149], v[156:157]
	ds_write_b128 v119, v[146:149]
.LBB0_351:
	s_or_b64 exec, exec, s[6:7]
	s_lshl_b32 s6, s68, 7
	s_cmp_eq_u32 s72, s68
	s_cbranch_scc1 .Lpa_w2ok
	v_or_b32_e32 v34, s6, v121
	v_lshlrev_b32_e32 v50, 2, v34
	v_mov_b32_e32 v51, v169
	v_lshl_add_u64 v[52:53], s[4:5], 0, v[50:51]
	v_add_co_u32_e32 v40, vcc, 0x1000, v52
	global_load_dword v228, v50, s[4:5]
	global_load_dword v230, v50, s[4:5] offset:2048
	v_addc_co_u32_e32 v41, vcc, 0, v53, vcc
	v_add_co_u32_e32 v42, vcc, s92, v52
	global_load_dword v232, v[40:41], off
	s_nop 0
	global_load_dword v234, v[40:41], off offset:2048
	v_addc_co_u32_e32 v43, vcc, 0, v53, vcc
	global_load_dword v229, v[42:43], off
	global_load_dword v231, v[42:43], off offset:2048
	v_add_co_u32_e32 v42, vcc, 0x3000, v52
	s_movk_i32 s0, 0x4000
	s_nop 0
	v_addc_co_u32_e32 v43, vcc, 0, v53, vcc
	v_add_co_u32_e32 v44, vcc, s0, v52
	s_movk_i32 s0, 0x6000
	s_nop 0
	v_addc_co_u32_e32 v45, vcc, 0, v53, vcc
	v_add_co_u32_e32 v48, vcc, 0x5000, v52
	global_load_dword v233, v[42:43], off
	global_load_dword v235, v[42:43], off offset:2048
	v_addc_co_u32_e32 v49, vcc, 0, v53, vcc
	v_add_co_u32_e32 v54, vcc, s0, v52
	global_load_dword v236, v[44:45], off
	s_nop 0
	global_load_dword v238, v[44:45], off offset:2048
	v_addc_co_u32_e32 v55, vcc, 0, v53, vcc
	v_add_co_u32_e32 v52, vcc, 0x7000, v52
	global_load_dword v240, v[48:49], off
	s_nop 0
	global_load_dword v242, v[48:49], off offset:2048
	v_addc_co_u32_e32 v53, vcc, 0, v53, vcc
	global_load_dword v237, v[54:55], off
	global_load_dword v239, v[54:55], off offset:2048
	global_load_dword v241, v[52:53], off
	global_load_dword v243, v[52:53], off offset:2048
	s_nop 0
	global_load_dword v158, v50, s[38:39]
	s_waitcnt vmcnt(0)
	s_mov_b32 s72, s68
.Lpa_w2ok:
	v_mov_b32_e32 v34, v228
	v_mov_b32_e32 v35, v229
	v_mov_b32_e32 v36, v230
	v_mov_b32_e32 v37, v231
	v_mov_b32_e32 v38, v232
	v_mov_b32_e32 v39, v233
	v_mov_b32_e32 v40, v234
	v_mov_b32_e32 v41, v235
	v_mov_b32_e32 v42, v236
	v_mov_b32_e32 v43, v237
	v_mov_b32_e32 v44, v238
	v_mov_b32_e32 v45, v239
	v_mov_b32_e32 v46, v240
	v_mov_b32_e32 v47, v241
	v_mov_b32_e32 v48, v242
	v_mov_b32_e32 v49, v243
	v_mov_b32_e32 v50, v158
	ds_write_b128 v133, v[194:197]
	ds_write_b128 v134, v[198:201]
	ds_write_b128 v135, v[202:205]
	ds_write_b128 v136, v[206:209]
	v_mov_b32_e32 v16, 0
	s_mov_b32 s7, 16
	v_mov_b32_e32 v17, v132
	v_mov_b32_e32 v18, v131
	s_waitcnt lgkmcnt(0)
	s_barrier
	s_add_i32 s98, s66, s82
	s_cmpk_gt_i32 s98, 0x1ff
	s_cbranch_scc1 .Lpa_nopf
	s_ashr_i32 s99, s98, 7
	s_lshl_b32 s99, s99, 11
	s_bfe_u32 s100, s98, 0x50002
	s_lshl_b32 s100, s100, 6
	s_or_b32 s99, s99, s100
	s_and_b32 s98, s98, 3
	s_lshl_b32 s73, s98, 8
	s_lshl_b32 s100, s99, 13
	s_add_u32 s100, s100, s73
	s_add_u32 s100, s24, s100
	s_addc_u32 s101, s25, 0
	global_load_dwordx4 v[178:181], v247, s[100:101] offset:2048
	global_load_dwordx4 v[182:185], v247, s[100:101] offset:2064
	global_load_dwordx4 v[186:189], v247, s[100:101] offset:3072
	global_load_dwordx4 v[190:193], v247, s[100:101] offset:3088
	s_add_u32 s73, s73, 0x1000
	s_add_u32 s100, s100, s73
	s_addc_u32 s101, s101, 0
	global_load_dwordx4 v[194:197], v248, s[100:101]
	s_add_u32 s100, s100, 0x20000
	s_addc_u32 s101, s101, 0
	global_load_dwordx4 v[198:201], v248, s[100:101]
	s_add_u32 s100, s100, 0x20000
	s_addc_u32 s101, s101, 0
	global_load_dwordx4 v[202:205], v248, s[100:101]
	s_add_u32 s100, s100, 0x20000
	s_addc_u32 s101, s101, 0
	global_load_dwordx4 v[206:209], v248, s[100:101]
	s_lshl_b32 s99, s99, 6
	s_add_u32 s100, s24, 0x0e9c4000
	s_addc_u32 s101, s25, 0
	s_add_u32 s100, s100, s99
	s_addc_u32 s101, s101, 0
	global_load_dwordx4 v[142:145], v249, s[100:101]
	s_add_u32 s100, s100, 0x84000
	s_addc_u32 s101, s101, 0
	global_load_dwordx4 v[146:149], v249, s[100:101]
	s_add_u32 s100, s100, 0x84000
	s_addc_u32 s101, s101, 0
	global_load_dwordx4 v[150:153], v249, s[100:101]
	s_add_u32 s100, s100, 0x84000
	s_addc_u32 s101, s101, 0
	global_load_dwordx4 v[154:157], v249, s[100:101]
; #define LAS __attribute__((address_space(3)))
; __device__ __forceinline__ float logsig_f(float z) { return fminf(z, 0.f) - __logf(1.f + __expf(-fabsf(z))); }
; __device__ __forceinline__ void gla_passA(LAS unsigned char* lds, int uidx, const bf16_t* PR, const float* GLRP, const float* w2, const float* gb,
;                                           bf16_t* SUB, float* EB, bf16_t* QT, bf16_t* AM, int tid, int wid, int lane) {
;     ...
;     { float run = 0.f;
; #pragma unroll 4
;       for (int i = 0; i < 16; ++i) { const int t = 16 * tg + i; const LAS f32x4* gr = (const LAS f32x4*)(Gs + t * 16); const f32x4 a0 = gr[0], a1 = gr[1], a2 = gr[2], a3 = gr[3];
;           float z = bias;
;           z += a0.x * wk[0] + a0.y * wk[1] + a0.z * wk[2] + a0.w * wk[3]; z += a1.x * wk[4] + a1.y * wk[5] + a1.z * wk[6] + a1.w * wk[7];
;           z += a2.x * wk[8] + a2.y * wk[9] + a2.z * wk[10] + a2.w * wk[11]; z += a3.x * wk[12] + a3.y * wk[13] + a3.z * wk[14] + a3.w * wk[15];
;           run += logsig_f(z) * (1.f / 16.f); Bc[t * 129 + kcol] = run; }
;       Tt[tg * 128 + kcol] = run; }
.Lpa_nopf:
.LBB0_352:
	v_add_u32_e32 v19, 0, v17
	v_add_u32_e32 v20, 0x1d700, v19
	v_add_u32_e32 v24, 0x1d710, v19
	v_add_u32_e32 v28, 0x1d720, v19
	v_add_u32_e32 v52, 0x1d730, v19
	ds_read_b128 v[20:23], v20
	ds_read_b128 v[24:27], v24
	ds_read_b128 v[28:31], v28
	ds_read_b128 v[52:55], v52
	v_add_u32_e32 v51, 0, v18
	s_waitcnt lgkmcnt(3)
	v_mov_b32_e32 v56, v20
	s_waitcnt lgkmcnt(2)
	v_mov_b32_e32 v57, v24
	v_mov_b32_e32 v24, v21
	v_pk_mul_f32 v[24:25], v[36:37], v[24:25]
	v_mov_b32_e32 v20, v22
	v_mov_b32_e32 v21, v26
	v_mov_b32_e32 v26, v23
	s_waitcnt lgkmcnt(0)
	v_mov_b32_e32 v23, v52
	v_mov_b32_e32 v52, v29
	v_pk_fma_f32 v[24:25], v[34:35], v[56:57], v[24:25]
	v_mov_b32_e32 v22, v28
	v_mov_b32_e32 v28, v30
	v_mov_b32_e32 v29, v54
	v_mov_b32_e32 v54, v31
	v_pk_mul_f32 v[30:31], v[44:45], v[52:53]
	v_pk_fma_f32 v[20:21], v[38:39], v[20:21], v[24:25]
	v_pk_fma_f32 v[22:23], v[42:43], v[22:23], v[30:31]
	v_pk_fma_f32 v[20:21], v[40:41], v[26:27], v[20:21]
	v_pk_fma_f32 v[22:23], v[46:47], v[28:29], v[22:23]
	v_add_f32_e32 v20, v50, v20
	v_pk_fma_f32 v[22:23], v[48:49], v[54:55], v[22:23]
	v_add_f32_e32 v20, v20, v21
	v_add_f32_e32 v20, v20, v22
	v_add_f32_e32 v20, v20, v23
	v_min_f32_e32 v21, 0, v20
	v_mul_f32_e64 v20, |v20|, s17
	v_exp_f32_e32 v20, v20
	v_add_u32_e32 v58, 0x1d740, v19
	v_add_u32_e32 v59, 0x1d750, v19
	v_add_u32_e32 v60, 0x1d760, v19
	v_add_f32_e32 v20, 1.0, v20
	v_cmp_gt_f32_e32 vcc, s14, v20
	v_add_u32_e32 v61, 0x1d770, v19
	v_add_u32_e32 v62, 0x1d780, v19
	v_cndmask_b32_e64 v22, 0, 32, vcc
	v_ldexp_f32 v20, v20, v22
	v_log_f32_e32 v20, v20
	v_cndmask_b32_e32 v22, 0, v218, vcc
	v_add_u32_e32 v63, 0x1d790, v19
	v_add_u32_e32 v64, 0x1d7a0, v19
	v_mul_f32_e32 v23, 0x3f317217, v20
	v_fma_f32 v23, v20, s18, -v23
	v_fmac_f32_e32 v23, 0x3377d1cf, v20
	v_fmac_f32_e32 v23, 0x3f317217, v20
	v_cmp_lt_f32_e64 vcc, |v20|, s19
	v_add_u32_e32 v65, 0x1d7b0, v19
	v_add_u32_e32 v66, 0x1d7c0, v19
	v_cndmask_b32_e32 v20, v20, v23, vcc
	v_sub_f32_e32 v20, v20, v22
	v_sub_f32_e32 v20, v21, v20
	v_fmac_f32_e32 v16, 0x3d800000, v20
	ds_write_b32 v51, v16
	ds_read_b128 v[20:23], v58
	ds_read_b128 v[24:27], v59
	ds_read_b128 v[28:31], v60
	ds_read_b128 v[52:55], v61
	v_add_u32_e32 v67, 0x1d7d0, v19
	s_waitcnt lgkmcnt(3)
	v_mov_b32_e32 v56, v20
	s_waitcnt lgkmcnt(2)
	v_mov_b32_e32 v57, v24
	v_mov_b32_e32 v24, v21
	v_pk_mul_f32 v[24:25], v[36:37], v[24:25]
	v_mov_b32_e32 v20, v22
	v_mov_b32_e32 v21, v26
	v_mov_b32_e32 v26, v23
	s_waitcnt lgkmcnt(0)
	v_mov_b32_e32 v23, v52
	v_mov_b32_e32 v52, v29
	v_pk_fma_f32 v[24:25], v[34:35], v[56:57], v[24:25]
	v_mov_b32_e32 v22, v28
	v_mov_b32_e32 v28, v30
	v_mov_b32_e32 v29, v54
	v_mov_b32_e32 v54, v31
	v_pk_mul_f32 v[30:31], v[44:45], v[52:53]
	v_pk_fma_f32 v[20:21], v[38:39], v[20:21], v[24:25]
	v_pk_fma_f32 v[22:23], v[42:43], v[22:23], v[30:31]
	v_pk_fma_f32 v[20:21], v[40:41], v[26:27], v[20:21]
	v_pk_fma_f32 v[22:23], v[46:47], v[28:29], v[22:23]
	v_add_f32_e32 v20, v50, v20
	v_pk_fma_f32 v[22:23], v[48:49], v[54:55], v[22:23]
	v_add_f32_e32 v20, v20, v21
	v_add_f32_e32 v20, v20, v22
	v_add_f32_e32 v20, v20, v23
	v_min_f32_e32 v21, 0, v20
	v_mul_f32_e64 v20, |v20|, s17
	v_exp_f32_e32 v20, v20
	v_add_u32_e32 v68, 0x1d7e0, v19
	v_add_u32_e32 v19, 0x1d7f0, v19
	s_add_i32 s7, s7, -4
	v_add_f32_e32 v20, 1.0, v20
	v_cmp_gt_f32_e32 vcc, s14, v20
	v_add_u32_e32 v18, 0x810, v18
	v_add_u32_e32 v17, 0x100, v17
	v_cndmask_b32_e64 v22, 0, 32, vcc
	v_ldexp_f32 v20, v20, v22
	v_log_f32_e32 v20, v20
	v_cndmask_b32_e32 v22, 0, v218, vcc
	s_cmp_eq_u32 s7, 0
	v_mul_f32_e32 v23, 0x3f317217, v20
	v_fma_f32 v23, v20, s18, -v23
	v_fmac_f32_e32 v23, 0x3377d1cf, v20
	v_fmac_f32_e32 v23, 0x3f317217, v20
	v_cmp_lt_f32_e64 vcc, |v20|, s19
	s_nop 1
	v_cndmask_b32_e32 v20, v20, v23, vcc
	v_sub_f32_e32 v20, v20, v22
	v_sub_f32_e32 v20, v21, v20
	v_fmac_f32_e32 v16, 0x3d800000, v20
	ds_write_b32 v51, v16 offset:516
	ds_read_b128 v[20:23], v62
	ds_read_b128 v[24:27], v63
	ds_read_b128 v[28:31], v64
	ds_read_b128 v[52:55], v65
	s_waitcnt lgkmcnt(3)
	v_mov_b32_e32 v56, v20
	s_waitcnt lgkmcnt(2)
	v_mov_b32_e32 v57, v24
	v_mov_b32_e32 v24, v21
	v_pk_mul_f32 v[24:25], v[36:37], v[24:25]
	v_mov_b32_e32 v20, v22
	v_mov_b32_e32 v21, v26
	v_mov_b32_e32 v26, v23
	s_waitcnt lgkmcnt(0)
	v_mov_b32_e32 v23, v52
	v_mov_b32_e32 v52, v29
	v_pk_fma_f32 v[24:25], v[34:35], v[56:57], v[24:25]
	v_mov_b32_e32 v22, v28
	v_mov_b32_e32 v28, v30
	v_mov_b32_e32 v29, v54
	v_mov_b32_e32 v54, v31
	v_pk_mul_f32 v[30:31], v[44:45], v[52:53]
	v_pk_fma_f32 v[20:21], v[38:39], v[20:21], v[24:25]
	v_pk_fma_f32 v[22:23], v[42:43], v[22:23], v[30:31]
	v_pk_fma_f32 v[20:21], v[40:41], v[26:27], v[20:21]
	v_pk_fma_f32 v[22:23], v[46:47], v[28:29], v[22:23]
	v_add_f32_e32 v20, v50, v20
	v_pk_fma_f32 v[22:23], v[48:49], v[54:55], v[22:23]
	v_add_f32_e32 v20, v20, v21
	v_add_f32_e32 v20, v20, v22
	v_add_f32_e32 v20, v20, v23
	v_min_f32_e32 v21, 0, v20
	v_mul_f32_e64 v20, |v20|, s17
	v_exp_f32_e32 v20, v20
	s_nop 0
	v_add_f32_e32 v20, 1.0, v20
	v_cmp_gt_f32_e32 vcc, s14, v20
	s_nop 1
	v_cndmask_b32_e64 v22, 0, 32, vcc
	v_ldexp_f32 v20, v20, v22
	v_log_f32_e32 v20, v20
	v_cndmask_b32_e32 v22, 0, v218, vcc
	v_mul_f32_e32 v23, 0x3f317217, v20
	v_fma_f32 v23, v20, s18, -v23
	v_fmac_f32_e32 v23, 0x3377d1cf, v20
	v_fmac_f32_e32 v23, 0x3f317217, v20
	v_cmp_lt_f32_e64 vcc, |v20|, s19
	s_nop 1
	v_cndmask_b32_e32 v20, v20, v23, vcc
	v_sub_f32_e32 v20, v20, v22
	v_sub_f32_e32 v20, v21, v20
	v_fmac_f32_e32 v16, 0x3d800000, v20
	ds_write_b32 v51, v16 offset:1032
	ds_read_b128 v[20:23], v66
	ds_read_b128 v[24:27], v67
	ds_read_b128 v[28:31], v68
	ds_read_b128 v[52:55], v19
	s_waitcnt lgkmcnt(3)
; __device__ __forceinline__ void gla_passA(LAS unsigned char* lds, int uidx, const bf16_t* PR, const float* GLRP, const float* w2, const float* gb,
;                                           bf16_t* SUB, float* EB, bf16_t* QT, bf16_t* AM, int tid, int wid, int lane) {
;     ...
;       for (int i = 0; i < 16; ++i) { const int t = 16 * tg + i; const LAS f32x4* gr = (const LAS f32x4*)(Gs + t * 16); const f32x4 a0 = gr[0], a1 = gr[1], a2 = gr[2], a3 = gr[3];
;           float z = bias;
;           z += a0.x * wk[0] + a0.y * wk[1] + a0.z * wk[2] + a0.w * wk[3]; z += a1.x * wk[4] + a1.y * wk[5] + a1.z * wk[6] + a1.w * wk[7];
;           z += a2.x * wk[8] + a2.y * wk[9] + a2.z * wk[10] + a2.w * wk[11]; z += a3.x * wk[12] + a3.y * wk[13] + a3.z * wk[14] + a3.w * wk[15];
;           run += logsig_f(z) * (1.f / 16.f); Bc[t * 129 + kcol] = run; }
;       Tt[tg * 128 + kcol] = run; }
;     __syncthreads();
;     {
;         const int j = tid >> 3, kr = (tid & 7) * 16, jg = j >> 4;
;         const float scale = 0.08838834764831845f;
;         u32x4 oq[2], ok[2], oh[2];
; #pragma unroll
;         for (int e4 = 0; e4 < 4; ++e4) {
;             const f32x4 t0 = *(const LAS f32x4*)(Tt + 0 * 128 + kr + 4 * e4), t1 = *(const LAS f32x4*)(Tt + 1 * 128 + kr + 4 * e4), t2 = *(const LAS f32x4*)(Tt + 2 * 128 + kr + 4 * e4), t3 = *(const LAS f32x4*)(Tt + 3 * 128 + kr + 4 * e4);
;             const f32x4 zz = {0.f, 0.f, 0.f, 0.f}; const f32x4 off = (jg > 0 ? t0 : zz) + (jg > 1 ? t1 : zz) + (jg > 2 ? t2 : zz), bc = (t0 + t1) + (t2 + t3);
; #pragma unroll
;             for (int eh = 0; eh < 2; ++eh) { const int e2 = 2 * e4 + eh; const unsigned qw = e2 < 4 ? qa[e2] : qb[e2 - 4], kw = e2 < 4 ? ka[e2] : kb[e2 - 4];
;                 const int k = kr + 2 * e2;
;                 const float b0 = Bc[j * 129 + k] + off[2 * eh], b1 = Bc[j * 129 + k + 1] + off[2 * eh + 1], c0 = bc[2 * eh], c1 = bc[2 * eh + 1];
;                 const float q0 = bf_lo(qw) * scale * __expf(b0), q1 = bf_hi(qw) * scale * __expf(b1);
;                 const float k0 = bf_lo(kw), k1 = bf_hi(kw);
;                 const unsigned pq = cvt_pk_bf16(q0, q1), pk = cvt_pk_bf16(k0 * __expf(-b0), k1 * __expf(-b1)), ph = cvt_pk_bf16(k0 * __expf(c0 - b0), k1 * __expf(c1 - b1));
;                 if (e2 < 4) { oq[0][e2] = pq; ok[0][e2] = pk; oh[0][e2] = ph; } else { oq[1][e2 - 4] = pq; ok[1][e2 - 4] = pk; oh[1][e2 - 4] = ph; } }
	v_mov_b32_e32 v56, v20
	s_waitcnt lgkmcnt(2)
	v_mov_b32_e32 v57, v24
	v_mov_b32_e32 v24, v21
	v_pk_mul_f32 v[24:25], v[36:37], v[24:25]
	v_mov_b32_e32 v20, v22
	v_mov_b32_e32 v21, v26
	v_mov_b32_e32 v26, v23
	s_waitcnt lgkmcnt(0)
	v_mov_b32_e32 v23, v52
	v_mov_b32_e32 v52, v29
	v_pk_fma_f32 v[24:25], v[34:35], v[56:57], v[24:25]
	v_mov_b32_e32 v22, v28
	v_mov_b32_e32 v28, v30
	v_mov_b32_e32 v29, v54
	v_mov_b32_e32 v54, v31
	v_pk_mul_f32 v[30:31], v[44:45], v[52:53]
	v_pk_fma_f32 v[20:21], v[38:39], v[20:21], v[24:25]
	v_pk_fma_f32 v[22:23], v[42:43], v[22:23], v[30:31]
	v_pk_fma_f32 v[20:21], v[40:41], v[26:27], v[20:21]
	v_pk_fma_f32 v[22:23], v[46:47], v[28:29], v[22:23]
	v_add_f32_e32 v19, v50, v20
	v_pk_fma_f32 v[22:23], v[48:49], v[54:55], v[22:23]
	v_add_f32_e32 v19, v19, v21
	v_add_f32_e32 v19, v19, v22
	v_add_f32_e32 v19, v19, v23
	v_mul_f32_e64 v20, |v19|, s17
	v_exp_f32_e32 v20, v20
	v_min_f32_e32 v19, 0, v19
	v_add_f32_e32 v20, 1.0, v20
	v_cmp_gt_f32_e32 vcc, s14, v20
	s_nop 1
	v_cndmask_b32_e64 v21, 0, 32, vcc
	v_ldexp_f32 v20, v20, v21
	v_log_f32_e32 v20, v20
	v_cndmask_b32_e32 v21, 0, v218, vcc
	v_mul_f32_e32 v22, 0x3f317217, v20
	v_fma_f32 v22, v20, s18, -v22
	v_fmac_f32_e32 v22, 0x3377d1cf, v20
	v_fmac_f32_e32 v22, 0x3f317217, v20
	v_cmp_lt_f32_e64 vcc, |v20|, s19
	s_nop 1
	v_cndmask_b32_e32 v20, v20, v22, vcc
	v_sub_f32_e32 v20, v20, v21
	v_sub_f32_e32 v19, v19, v20
	v_fmac_f32_e32 v16, 0x3d800000, v19
	ds_write_b32 v51, v16 offset:1548
	s_cbranch_scc0 .LBB0_352
	ds_write_b32 v122, v16
	s_waitcnt lgkmcnt(0)
	s_barrier
	ds_read_b128 v[16:19], v123
	ds_read_b128 v[20:23], v124
	ds_read_b128 v[24:27], v125
	ds_read_b128 v[28:31], v126
	s_lshl_b32 s10, s6, 1
	s_waitcnt lgkmcnt(3)
	v_cndmask_b32_e64 v35, 0, v19, s[44:45]
	v_cndmask_b32_e64 v34, 0, v18, s[44:45]
	v_cndmask_b32_e64 v37, 0, v17, s[44:45]
	v_cndmask_b32_e64 v36, 0, v16, s[44:45]
	s_waitcnt lgkmcnt(2)
	v_cndmask_b32_e64 v41, 0, v21, s[46:47]
	v_cndmask_b32_e64 v40, 0, v20, s[46:47]
	v_pk_add_f32 v[18:19], v[18:19], v[22:23]
	v_pk_add_f32 v[16:17], v[16:17], v[20:21]
	s_waitcnt lgkmcnt(0)
	v_pk_add_f32 v[20:21], v[26:27], v[30:31]
	v_cndmask_b32_e64 v39, 0, v23, s[46:47]
	v_pk_add_f32 v[18:19], v[18:19], v[20:21]
	ds_read2_b32 v[20:21], v127 offset1:1
	v_cndmask_b32_e64 v38, 0, v22, s[46:47]
	v_pk_add_f32 v[36:37], v[36:37], v[40:41]
	v_pk_add_f32 v[34:35], v[34:35], v[38:39]
	v_cndmask_b32_e64 v39, 0, v25, s[48:49]
	v_cndmask_b32_e64 v38, 0, v24, s[48:49]
	v_pk_add_f32 v[36:37], v[36:37], v[38:39]
	v_pk_add_f32 v[22:23], v[24:25], v[28:29]
	s_waitcnt lgkmcnt(0)
	v_add_f32_e32 v20, v20, v36
	v_pk_add_f32 v[16:17], v[16:17], v[22:23]
	v_mul_f32_e32 v23, 0x3fb8aa3b, v20
	v_exp_f32_e32 v23, v23
	v_lshlrev_b32_e32 v22, 16, v12
	v_add_f32_e32 v21, v37, v21
	v_mul_f32_e32 v22, 0x3db504f3, v22
	v_mul_f32_e32 v22, v22, v23
	v_mul_f32_e32 v23, 0x3fb8aa3b, v21
	v_exp_f32_e32 v23, v23
	v_and_b32_e32 v12, 0xffff0000, v12
	v_mul_f32_e32 v12, 0x3db504f3, v12
	v_sub_f32_e32 v16, v16, v20
	v_mul_f32_e32 v12, v12, v23
	v_lshlrev_b32_e32 v23, 16, v8
	v_and_b32_e32 v24, 0xffff0000, v8
	v_cvt_pk_bf16_f32 v8, v22, v12
	v_mul_f32_e32 v12, 0xbfb8aa3b, v20
	v_mul_f32_e32 v16, 0x3fb8aa3b, v16
	v_sub_f32_e32 v17, v17, v21
	v_exp_f32_e32 v12, v12
	v_mul_f32_e32 v22, 0xbfb8aa3b, v21
	v_exp_f32_e32 v16, v16
	v_mul_f32_e32 v17, 0x3fb8aa3b, v17
	v_exp_f32_e32 v22, v22
	v_exp_f32_e32 v17, v17
	v_mul_f32_e32 v12, v12, v23
	v_mul_f32_e32 v16, v16, v23
	v_mul_f32_e32 v22, v22, v24
	v_cvt_pk_bf16_f32 v12, v12, v22
	v_mul_f32_e32 v17, v17, v24
	v_cvt_pk_bf16_f32 v16, v16, v17
	ds_read2_b32 v[20:21], v127 offset0:2 offset1:3
	v_cndmask_b32_e64 v41, 0, v27, s[48:49]
	v_cndmask_b32_e64 v40, 0, v26, s[48:49]
	v_pk_add_f32 v[34:35], v[34:35], v[40:41]
	v_and_b32_e32 v23, 0xffff0000, v9
	s_waitcnt lgkmcnt(0)
	v_add_f32_e32 v17, v34, v20
	v_mul_f32_e32 v22, 0x3fb8aa3b, v17
	v_exp_f32_e32 v22, v22
	v_add_f32_e32 v20, v35, v21
	v_lshlrev_b32_e32 v21, 16, v13
	v_mul_f32_e32 v21, 0x3db504f3, v21
	v_mul_f32_e32 v21, v21, v22
	v_mul_f32_e32 v22, 0x3fb8aa3b, v20
	v_exp_f32_e32 v22, v22
	v_and_b32_e32 v13, 0xffff0000, v13
	v_mul_f32_e32 v13, 0x3db504f3, v13
	s_lshl_b32 s7, s67, 2
	v_mul_f32_e32 v13, v13, v22
	v_lshlrev_b32_e32 v22, 16, v9
	v_cvt_pk_bf16_f32 v9, v21, v13
	v_mul_f32_e32 v13, 0xbfb8aa3b, v17
	v_sub_f32_e32 v17, v18, v17
	v_sub_f32_e32 v18, v19, v20
	v_mul_f32_e32 v21, 0xbfb8aa3b, v20
	v_mul_f32_e32 v17, 0x3fb8aa3b, v17
	v_mul_f32_e32 v18, 0x3fb8aa3b, v18
	v_exp_f32_e32 v13, v13
	v_exp_f32_e32 v21, v21
	v_exp_f32_e32 v17, v17
	v_exp_f32_e32 v18, v18
	v_mul_f32_e32 v13, v13, v22
	v_mul_f32_e32 v21, v21, v23
	v_mul_f32_e32 v17, v17, v22
	v_mul_f32_e32 v18, v18, v23
	v_cvt_pk_bf16_f32 v13, v13, v21
	v_cvt_pk_bf16_f32 v17, v17, v18
	ds_read_b128 v[18:21], v123 offset:16
	ds_read_b128 v[22:25], v124 offset:16
	ds_read_b128 v[26:29], v125 offset:16
	ds_read_b128 v[34:37], v126 offset:16
	s_or_b32 s86, s7, s68
	s_waitcnt lgkmcnt(3)
	v_cndmask_b32_e64 v31, 0, v21, s[44:45]
	v_cndmask_b32_e64 v30, 0, v20, s[44:45]
	v_cndmask_b32_e64 v39, 0, v19, s[44:45]
	v_cndmask_b32_e64 v38, 0, v18, s[44:45]
	s_waitcnt lgkmcnt(2)
	v_cndmask_b32_e64 v43, 0, v23, s[46:47]
	v_cndmask_b32_e64 v42, 0, v22, s[46:47]
	v_pk_add_f32 v[20:21], v[20:21], v[24:25]
	v_pk_add_f32 v[18:19], v[18:19], v[22:23]
	s_waitcnt lgkmcnt(0)
	v_pk_add_f32 v[22:23], v[28:29], v[36:37]
	v_cndmask_b32_e64 v41, 0, v25, s[46:47]
	v_pk_add_f32 v[20:21], v[20:21], v[22:23]
	ds_read2_b32 v[22:23], v127 offset0:4 offset1:5
	v_cndmask_b32_e64 v40, 0, v24, s[46:47]
	v_pk_add_f32 v[38:39], v[38:39], v[42:43]
	v_pk_add_f32 v[30:31], v[30:31], v[40:41]
	v_cndmask_b32_e64 v41, 0, v27, s[48:49]
	v_cndmask_b32_e64 v40, 0, v26, s[48:49]
	v_pk_add_f32 v[38:39], v[38:39], v[40:41]
	v_pk_add_f32 v[24:25], v[26:27], v[34:35]
	s_waitcnt lgkmcnt(0)
; __device__ __forceinline__ unsigned cvt_pk_bf16(float lo, float hi) { unsigned r; asm volatile("v_cvt_pk_bf16_f32 %0, %1, %2" : "=v"(r) : "v"(lo), "v"(hi)); return r; }
; #define LAS __attribute__((address_space(3)))
; __device__ __forceinline__ float bf_lo(unsigned w) { return __uint_as_float(w << 16); }
; __device__ __forceinline__ float bf_hi(unsigned w) { return __uint_as_float(w & 0xffff0000u); }
; __device__ __forceinline__ void gla_passA(LAS unsigned char* lds, int uidx, const bf16_t* PR, const float* GLRP, const float* w2, const float* gb,
;                                           bf16_t* SUB, float* EB, bf16_t* QT, bf16_t* AM, int tid, int wid, int lane) {
;     ...
;         for (int e4 = 0; e4 < 4; ++e4) {
;             const f32x4 t0 = *(const LAS f32x4*)(Tt + 0 * 128 + kr + 4 * e4), t1 = *(const LAS f32x4*)(Tt + 1 * 128 + kr + 4 * e4), t2 = *(const LAS f32x4*)(Tt + 2 * 128 + kr + 4 * e4), t3 = *(const LAS f32x4*)(Tt + 3 * 128 + kr + 4 * e4);
;             const f32x4 zz = {0.f, 0.f, 0.f, 0.f}; const f32x4 off = (jg > 0 ? t0 : zz) + (jg > 1 ? t1 : zz) + (jg > 2 ? t2 : zz), bc = (t0 + t1) + (t2 + t3);
; #pragma unroll
;             for (int eh = 0; eh < 2; ++eh) { const int e2 = 2 * e4 + eh; const unsigned qw = e2 < 4 ? qa[e2] : qb[e2 - 4], kw = e2 < 4 ? ka[e2] : kb[e2 - 4];
;                 const int k = kr + 2 * e2;
;                 const float b0 = Bc[j * 129 + k] + off[2 * eh], b1 = Bc[j * 129 + k + 1] + off[2 * eh + 1], c0 = bc[2 * eh], c1 = bc[2 * eh + 1];
;                 const float q0 = bf_lo(qw) * scale * __expf(b0), q1 = bf_hi(qw) * scale * __expf(b1);
;                 const float k0 = bf_lo(kw), k1 = bf_hi(kw);
;                 const unsigned pq = cvt_pk_bf16(q0, q1), pk = cvt_pk_bf16(k0 * __expf(-b0), k1 * __expf(-b1)), ph = cvt_pk_bf16(k0 * __expf(c0 - b0), k1 * __expf(c1 - b1));
;                 if (e2 < 4) { oq[0][e2] = pq; ok[0][e2] = pk; oh[0][e2] = ph; } else { oq[1][e2 - 4] = pq; ok[1][e2 - 4] = pk; oh[1][e2 - 4] = ph; } }
	v_add_f32_e32 v22, v22, v38
	v_pk_add_f32 v[18:19], v[18:19], v[24:25]
	v_mul_f32_e32 v25, 0x3fb8aa3b, v22
	v_exp_f32_e32 v25, v25
	v_lshlrev_b32_e32 v24, 16, v14
	v_add_f32_e32 v23, v39, v23
	v_mul_f32_e32 v24, 0x3db504f3, v24
	v_mul_f32_e32 v24, v24, v25
	v_mul_f32_e32 v25, 0x3fb8aa3b, v23
	v_exp_f32_e32 v25, v25
	v_and_b32_e32 v14, 0xffff0000, v14
	v_mul_f32_e32 v14, 0x3db504f3, v14
	v_sub_f32_e32 v18, v18, v22
	v_mul_f32_e32 v14, v14, v25
	v_lshlrev_b32_e32 v25, 16, v10
	v_and_b32_e32 v26, 0xffff0000, v10
	v_cvt_pk_bf16_f32 v10, v24, v14
	v_mul_f32_e32 v14, 0xbfb8aa3b, v22
	v_mul_f32_e32 v18, 0x3fb8aa3b, v18
	v_sub_f32_e32 v19, v19, v23
	v_exp_f32_e32 v14, v14
	v_mul_f32_e32 v24, 0xbfb8aa3b, v23
	v_exp_f32_e32 v18, v18
	v_mul_f32_e32 v19, 0x3fb8aa3b, v19
	v_exp_f32_e32 v24, v24
	v_exp_f32_e32 v19, v19
	v_mul_f32_e32 v14, v14, v25
	v_mul_f32_e32 v18, v18, v25
	v_mul_f32_e32 v24, v24, v26
	v_cvt_pk_bf16_f32 v14, v14, v24
	v_mul_f32_e32 v19, v19, v26
	v_cvt_pk_bf16_f32 v18, v18, v19
	ds_read2_b32 v[22:23], v127 offset0:6 offset1:7
	v_cndmask_b32_e64 v43, 0, v29, s[48:49]
	v_cndmask_b32_e64 v42, 0, v28, s[48:49]
	v_pk_add_f32 v[30:31], v[30:31], v[42:43]
	v_and_b32_e32 v25, 0xffff0000, v11
	s_waitcnt lgkmcnt(0)
	v_add_f32_e32 v19, v30, v22
	v_mul_f32_e32 v24, 0x3fb8aa3b, v19
	v_exp_f32_e32 v24, v24
	v_add_f32_e32 v22, v31, v23
	v_lshlrev_b32_e32 v23, 16, v15
	v_mul_f32_e32 v23, 0x3db504f3, v23
	v_mul_f32_e32 v23, v23, v24
	v_mul_f32_e32 v24, 0x3fb8aa3b, v22
	v_exp_f32_e32 v24, v24
	v_and_b32_e32 v15, 0xffff0000, v15
	v_mul_f32_e32 v15, 0x3db504f3, v15
	v_mul_f32_e32 v15, v15, v24
	v_lshlrev_b32_e32 v24, 16, v11
	v_cvt_pk_bf16_f32 v11, v23, v15
	v_mul_f32_e32 v15, 0xbfb8aa3b, v19
	v_sub_f32_e32 v19, v20, v19
	v_sub_f32_e32 v20, v21, v22
	v_mul_f32_e32 v23, 0xbfb8aa3b, v22
	v_mul_f32_e32 v19, 0x3fb8aa3b, v19
	v_mul_f32_e32 v20, 0x3fb8aa3b, v20
	v_exp_f32_e32 v15, v15
	v_exp_f32_e32 v23, v23
	v_exp_f32_e32 v19, v19
	v_exp_f32_e32 v20, v20
	v_mul_f32_e32 v15, v15, v24
	v_mul_f32_e32 v23, v23, v25
	v_mul_f32_e32 v19, v19, v24
	v_mul_f32_e32 v20, v20, v25
	v_cvt_pk_bf16_f32 v15, v15, v23
	v_cvt_pk_bf16_f32 v19, v19, v20
	ds_read_b128 v[20:23], v123 offset:32
	ds_read_b128 v[24:27], v124 offset:32
	ds_read_b128 v[28:31], v125 offset:32
	ds_read_b128 v[34:37], v126 offset:32
	s_waitcnt lgkmcnt(3)
	v_cndmask_b32_e64 v39, 0, v23, s[44:45]
	v_cndmask_b32_e64 v38, 0, v22, s[44:45]
	v_cndmask_b32_e64 v41, 0, v21, s[44:45]
	v_cndmask_b32_e64 v40, 0, v20, s[44:45]
	s_waitcnt lgkmcnt(2)
	v_cndmask_b32_e64 v45, 0, v25, s[46:47]
	v_cndmask_b32_e64 v44, 0, v24, s[46:47]
	v_pk_add_f32 v[22:23], v[22:23], v[26:27]
	v_pk_add_f32 v[20:21], v[20:21], v[24:25]
	s_waitcnt lgkmcnt(0)
	v_pk_add_f32 v[24:25], v[30:31], v[36:37]
	v_cndmask_b32_e64 v43, 0, v27, s[46:47]
	v_pk_add_f32 v[22:23], v[22:23], v[24:25]
	ds_read2_b32 v[24:25], v127 offset0:8 offset1:9
	v_cndmask_b32_e64 v42, 0, v26, s[46:47]
	v_pk_add_f32 v[40:41], v[40:41], v[44:45]
	v_pk_add_f32 v[38:39], v[38:39], v[42:43]
	v_cndmask_b32_e64 v43, 0, v29, s[48:49]
	v_cndmask_b32_e64 v42, 0, v28, s[48:49]
	v_pk_add_f32 v[40:41], v[40:41], v[42:43]
	v_pk_add_f32 v[26:27], v[28:29], v[34:35]
	s_waitcnt lgkmcnt(0)
	v_add_f32_e32 v24, v24, v40
	v_pk_add_f32 v[20:21], v[20:21], v[26:27]
	v_mul_f32_e32 v27, 0x3fb8aa3b, v24
	v_exp_f32_e32 v27, v27
	v_lshlrev_b32_e32 v26, 16, v4
	v_add_f32_e32 v25, v41, v25
	v_mul_f32_e32 v26, 0x3db504f3, v26
	v_mul_f32_e32 v26, v26, v27
	v_mul_f32_e32 v27, 0x3fb8aa3b, v25
	v_exp_f32_e32 v27, v27
	v_and_b32_e32 v4, 0xffff0000, v4
	v_mul_f32_e32 v4, 0x3db504f3, v4
	v_sub_f32_e32 v20, v20, v24
	v_mul_f32_e32 v4, v4, v27
	v_lshlrev_b32_e32 v27, 16, v0
	v_and_b32_e32 v28, 0xffff0000, v0
	v_cvt_pk_bf16_f32 v0, v26, v4
	v_mul_f32_e32 v4, 0xbfb8aa3b, v24
	v_mul_f32_e32 v20, 0x3fb8aa3b, v20
	v_sub_f32_e32 v21, v21, v25
	v_exp_f32_e32 v4, v4
	v_mul_f32_e32 v26, 0xbfb8aa3b, v25
	v_exp_f32_e32 v20, v20
	v_mul_f32_e32 v21, 0x3fb8aa3b, v21
	v_exp_f32_e32 v26, v26
	v_exp_f32_e32 v21, v21
	v_mul_f32_e32 v4, v4, v27
	v_mul_f32_e32 v20, v20, v27
	v_mul_f32_e32 v26, v26, v28
	v_cvt_pk_bf16_f32 v4, v4, v26
	v_mul_f32_e32 v21, v21, v28
	v_cvt_pk_bf16_f32 v20, v20, v21
	ds_read2_b32 v[24:25], v127 offset0:10 offset1:11
	v_cndmask_b32_e64 v45, 0, v31, s[48:49]
	v_cndmask_b32_e64 v44, 0, v30, s[48:49]
	v_pk_add_f32 v[38:39], v[38:39], v[44:45]
	v_and_b32_e32 v27, 0xffff0000, v1
	s_waitcnt lgkmcnt(0)
; __device__ __forceinline__ unsigned cvt_pk_bf16(float lo, float hi) { unsigned r; asm volatile("v_cvt_pk_bf16_f32 %0, %1, %2" : "=v"(r) : "v"(lo), "v"(hi)); return r; }
; #define LAS __attribute__((address_space(3)))
; __device__ __forceinline__ void gla_passA(LAS unsigned char* lds, int uidx, const bf16_t* PR, const float* GLRP, const float* w2, const float* gb,
;                                           bf16_t* SUB, float* EB, bf16_t* QT, bf16_t* AM, int tid, int wid, int lane) {
;     ...
;         for (int e4 = 0; e4 < 4; ++e4) {
;             const f32x4 t0 = *(const LAS f32x4*)(Tt + 0 * 128 + kr + 4 * e4), t1 = *(const LAS f32x4*)(Tt + 1 * 128 + kr + 4 * e4), t2 = *(const LAS f32x4*)(Tt + 2 * 128 + kr + 4 * e4), t3 = *(const LAS f32x4*)(Tt + 3 * 128 + kr + 4 * e4);
;             const f32x4 zz = {0.f, 0.f, 0.f, 0.f}; const f32x4 off = (jg > 0 ? t0 : zz) + (jg > 1 ? t1 : zz) + (jg > 2 ? t2 : zz), bc = (t0 + t1) + (t2 + t3);
; #pragma unroll
;             for (int eh = 0; eh < 2; ++eh) { const int e2 = 2 * e4 + eh; const unsigned qw = e2 < 4 ? qa[e2] : qb[e2 - 4], kw = e2 < 4 ? ka[e2] : kb[e2 - 4];
;                 const int k = kr + 2 * e2;
;                 const float b0 = Bc[j * 129 + k] + off[2 * eh], b1 = Bc[j * 129 + k + 1] + off[2 * eh + 1], c0 = bc[2 * eh], c1 = bc[2 * eh + 1];
;                 const float q0 = bf_lo(qw) * scale * __expf(b0), q1 = bf_hi(qw) * scale * __expf(b1);
;                 const float k0 = bf_lo(kw), k1 = bf_hi(kw);
;                 const unsigned pq = cvt_pk_bf16(q0, q1), pk = cvt_pk_bf16(k0 * __expf(-b0), k1 * __expf(-b1)), ph = cvt_pk_bf16(k0 * __expf(c0 - b0), k1 * __expf(c1 - b1));
;                 if (e2 < 4) { oq[0][e2] = pq; ok[0][e2] = pk; oh[0][e2] = ph; } else { oq[1][e2 - 4] = pq; ok[1][e2 - 4] = pk; oh[1][e2 - 4] = ph; } }
;         }
;         *(LAS u32x4*)(Qs + j * 136 + kr) = oq[0]; *(LAS u32x4*)(Qs + j * 136 + kr + 8) = oq[1];
;         *(LAS u32x4*)(Ks + j * 136 + kr) = ok[0]; *(LAS u32x4*)(Ks + j * 136 + kr + 8) = ok[1];
;         *(LAS u32x4*)(Kh + j * 136 + kr) = oh[0]; *(LAS u32x4*)(Kh + j * 136 + kr + 8) = oh[1];
;         bf16_t* qt = QT + (size_t)(tok0 + j) * QKD + h * DK + kr; *(u32x4*)qt = oq[0]; *(u32x4*)(qt + 8) = oq[1];
;         if (tid < DK) EB[((size_t)bh * NCH + c) * DK + tid] = __expf((Tt[tid] + Tt[128 + tid]) + (Tt[256 + tid] + Tt[384 + tid]));
	v_add_f32_e32 v21, v38, v24
	v_mul_f32_e32 v26, 0x3fb8aa3b, v21
	v_exp_f32_e32 v26, v26
	v_add_f32_e32 v24, v39, v25
	v_lshlrev_b32_e32 v25, 16, v5
	v_mul_f32_e32 v25, 0x3db504f3, v25
	v_mul_f32_e32 v25, v25, v26
	v_mul_f32_e32 v26, 0x3fb8aa3b, v24
	v_exp_f32_e32 v26, v26
	v_and_b32_e32 v5, 0xffff0000, v5
	v_mul_f32_e32 v5, 0x3db504f3, v5
	v_mul_f32_e32 v5, v5, v26
	v_lshlrev_b32_e32 v26, 16, v1
	v_cvt_pk_bf16_f32 v1, v25, v5
	v_mul_f32_e32 v5, 0xbfb8aa3b, v21
	v_sub_f32_e32 v21, v22, v21
	v_sub_f32_e32 v22, v23, v24
	v_mul_f32_e32 v25, 0xbfb8aa3b, v24
	v_mul_f32_e32 v21, 0x3fb8aa3b, v21
	v_mul_f32_e32 v22, 0x3fb8aa3b, v22
	v_exp_f32_e32 v5, v5
	v_exp_f32_e32 v25, v25
	v_exp_f32_e32 v21, v21
	v_exp_f32_e32 v22, v22
	v_mul_f32_e32 v5, v5, v26
	v_mul_f32_e32 v25, v25, v27
	v_mul_f32_e32 v21, v21, v26
	v_mul_f32_e32 v22, v22, v27
	v_cvt_pk_bf16_f32 v5, v5, v25
	v_cvt_pk_bf16_f32 v21, v21, v22
	ds_read_b128 v[22:25], v123 offset:48
	ds_read_b128 v[26:29], v124 offset:48
	ds_read_b128 v[34:37], v125 offset:48
	ds_read_b128 v[38:41], v126 offset:48
	s_waitcnt lgkmcnt(3)
	v_cndmask_b32_e64 v31, 0, v25, s[44:45]
	v_cndmask_b32_e64 v30, 0, v24, s[44:45]
	v_cndmask_b32_e64 v43, 0, v23, s[44:45]
	v_cndmask_b32_e64 v42, 0, v22, s[44:45]
	s_waitcnt lgkmcnt(2)
	v_cndmask_b32_e64 v47, 0, v27, s[46:47]
	v_cndmask_b32_e64 v46, 0, v26, s[46:47]
	v_pk_add_f32 v[24:25], v[24:25], v[28:29]
	v_pk_add_f32 v[22:23], v[22:23], v[26:27]
	s_waitcnt lgkmcnt(0)
	v_pk_add_f32 v[26:27], v[36:37], v[40:41]
	v_cndmask_b32_e64 v45, 0, v29, s[46:47]
	v_pk_add_f32 v[24:25], v[24:25], v[26:27]
	ds_read2_b32 v[26:27], v127 offset0:12 offset1:13
	v_cndmask_b32_e64 v44, 0, v28, s[46:47]
	v_pk_add_f32 v[42:43], v[42:43], v[46:47]
	v_pk_add_f32 v[30:31], v[30:31], v[44:45]
	v_cndmask_b32_e64 v45, 0, v35, s[48:49]
	v_cndmask_b32_e64 v44, 0, v34, s[48:49]
	v_pk_add_f32 v[42:43], v[42:43], v[44:45]
	v_pk_add_f32 v[28:29], v[34:35], v[38:39]
	s_waitcnt lgkmcnt(0)
	v_add_f32_e32 v26, v26, v42
	v_pk_add_f32 v[22:23], v[22:23], v[28:29]
	v_mul_f32_e32 v29, 0x3fb8aa3b, v26
	v_exp_f32_e32 v29, v29
	v_lshlrev_b32_e32 v28, 16, v6
	v_add_f32_e32 v27, v43, v27
	v_mul_f32_e32 v28, 0x3db504f3, v28
	v_mul_f32_e32 v28, v28, v29
	v_mul_f32_e32 v29, 0x3fb8aa3b, v27
	v_exp_f32_e32 v29, v29
	v_and_b32_e32 v6, 0xffff0000, v6
	v_mul_f32_e32 v6, 0x3db504f3, v6
	v_sub_f32_e32 v22, v22, v26
	v_mul_f32_e32 v6, v6, v29
	v_lshlrev_b32_e32 v29, 16, v2
	v_and_b32_e32 v34, 0xffff0000, v2
	v_cvt_pk_bf16_f32 v2, v28, v6
	v_mul_f32_e32 v6, 0xbfb8aa3b, v26
	v_mul_f32_e32 v22, 0x3fb8aa3b, v22
	v_sub_f32_e32 v23, v23, v27
	v_exp_f32_e32 v6, v6
	v_mul_f32_e32 v28, 0xbfb8aa3b, v27
	v_exp_f32_e32 v22, v22
	v_mul_f32_e32 v23, 0x3fb8aa3b, v23
	v_exp_f32_e32 v28, v28
	v_exp_f32_e32 v23, v23
	v_mul_f32_e32 v6, v6, v29
	v_mul_f32_e32 v22, v22, v29
	v_mul_f32_e32 v28, v28, v34
	v_cvt_pk_bf16_f32 v6, v6, v28
	v_mul_f32_e32 v23, v23, v34
	v_cvt_pk_bf16_f32 v22, v22, v23
	ds_read2_b32 v[26:27], v127 offset0:14 offset1:15
	v_cndmask_b32_e64 v47, 0, v37, s[48:49]
	v_cndmask_b32_e64 v46, 0, v36, s[48:49]
	v_pk_add_f32 v[30:31], v[30:31], v[46:47]
	v_and_b32_e32 v29, 0xffff0000, v3
	s_waitcnt lgkmcnt(0)
	v_add_f32_e32 v23, v30, v26
	v_mul_f32_e32 v28, 0x3fb8aa3b, v23
	v_exp_f32_e32 v28, v28
	v_add_f32_e32 v26, v31, v27
	v_lshlrev_b32_e32 v27, 16, v7
	v_mul_f32_e32 v27, 0x3db504f3, v27
	v_mul_f32_e32 v27, v27, v28
	v_mul_f32_e32 v28, 0x3fb8aa3b, v26
	v_exp_f32_e32 v28, v28
	v_and_b32_e32 v7, 0xffff0000, v7
	v_mul_f32_e32 v7, 0x3db504f3, v7
	v_mul_f32_e32 v7, v7, v28
	v_lshlrev_b32_e32 v28, 16, v3
	v_cvt_pk_bf16_f32 v3, v27, v7
	v_mul_f32_e32 v7, 0xbfb8aa3b, v23
	v_sub_f32_e32 v23, v24, v23
	v_mul_f32_e32 v23, 0x3fb8aa3b, v23
	v_sub_f32_e32 v24, v25, v26
	v_exp_f32_e32 v7, v7
	v_mul_f32_e32 v27, 0xbfb8aa3b, v26
	v_exp_f32_e32 v23, v23
	v_mul_f32_e32 v24, 0x3fb8aa3b, v24
	v_exp_f32_e32 v27, v27
	v_exp_f32_e32 v24, v24
	v_mul_f32_e32 v7, v7, v28
	v_mul_f32_e32 v23, v23, v28
	v_mul_f32_e32 v27, v27, v29
	v_cvt_pk_bf16_f32 v7, v7, v27
	v_mul_f32_e32 v24, v24, v29
	v_cvt_pk_bf16_f32 v23, v23, v24
	ds_write_b128 v128, v[8:11] offset:33536
	ds_write_b128 v128, v[0:3] offset:33552
	ds_write_b128 v128, v[12:15] offset:50944
	ds_write_b128 v128, v[4:7] offset:50960
	ds_write_b128 v129, v[16:19]
	ds_write_b128 v129, v[20:23] offset:16
	v_lshlrev_b64 v[4:5], 10, v[32:33]
	v_lshl_add_u64 v[4:5], s[34:35], 0, v[4:5]
	v_lshl_add_u64 v[4:5], v[4:5], 0, s[10:11]
	v_lshl_add_u64 v[4:5], v[4:5], 0, v[168:169]
	global_store_dwordx4 v[4:5], v[8:11], off
	global_store_dwordx4 v[4:5], v[0:3], off offset:16
	s_and_saveexec_b64 s[6:7], s[42:43]
	s_xor_b64 s[6:7], exec, s[6:7]
	s_ashr_i32 s87, s86, 31
	s_or_saveexec_b64 s[6:7], s[6:7]
	v_mov_b64_e32 v[108:109], s[86:87]
	s_xor_b64 exec, exec, s[6:7]
	s_cbranch_execz .LBB0_348
	ds_read2st64_b32 v[0:1], v122 offset1:2
	ds_read2st64_b32 v[2:3], v122 offset0:4 offset1:6
	s_ashr_i32 s87, s86, 31
	s_lshl_b64 s[68:69], s[86:87], 14
	s_add_u32 s10, s9, s68
	s_waitcnt lgkmcnt(1)
	v_mov_b32_e32 v4, v0
	s_waitcnt lgkmcnt(0)
	v_mov_b32_e32 v5, v2
	v_mov_b32_e32 v2, v1
	v_pk_add_f32 v[0:1], v[4:5], v[2:3]
	s_addc_u32 s67, s30, s69
	v_add_f32_e32 v0, v0, v1
	v_mul_f32_e32 v0, 0x3fb8aa3b, v0
	v_exp_f32_e32 v2, v0
	s_lshl_b32 s68, s31, 9
	s_add_u32 s68, s10, s68
	s_addc_u32 s69, s67, 0
	v_lshl_add_u64 v[0:1], v[112:113], 2, s[68:69]
	v_mov_b64_e32 v[108:109], s[86:87]
	global_store_dword v[0:1], v2, off
	s_branch .LBB0_348
